# global loads + SGPR-base DMA form + K-loop setprio and redundant post-barrier waits removed
# speedup vs baseline: 1.0131x; 1.0125x over previous
.LBB0_324:
	s_add_i32 vcc_lo, s66, 2
	s_add_u32 s34, s8, 0xfff00080
	s_addc_u32 s35, s9, -1
	s_add_i32 s89, 0, 0x10000
	s_cmp_eq_u32 s59, s66
	s_cselect_b32 s95, s65, s35
	s_cselect_b32 s94, s64, s34
	v_add_u32_e32 v0, s89, v217
	s_cselect_b32 s67, s53, s80
	s_cselect_b32 s66, s52, s70
	s_add_i32 vcc_hi, 0, 0x14000
	ds_read_b128 v[132:135], v0
	ds_read_b128 v[136:139], v0 offset:1024
	ds_read_b128 v[140:143], v0 offset:2048
	ds_read_b128 v[144:147], v0 offset:3072
	v_add_u32_e32 v0, vcc_hi, v217
	ds_read_b128 v[148:151], v0
	ds_read_b128 v[152:155], v0 offset:1024
	ds_read_b128 v[156:159], v0 offset:2048
	ds_read_b128 v[160:163], v0 offset:3072
	v_add_u32_e32 v0, 0, v216
	s_add_i32 m0, s29, 0xc000
	ds_read_b128 v[164:167], v0
	ds_read_b128 v[168:171], v0 offset:1024
	ds_read_b128 v[172:175], v0 offset:2048
	ds_read_b128 v[176:179], v0 offset:3072
	ds_read_b128 v[180:183], v0 offset:4096
	ds_read_b128 v[184:187], v0 offset:5120
	ds_read_b128 v[188:191], v0 offset:6144
	ds_read_b128 v[250:253], v0 offset:7168
	global_load_lds_dwordx4 v204, s[8:9]
	s_add_i32 m0, s29, 0xe000
	s_nop 0
	global_load_lds_dwordx4 v206, s[8:9]
	s_waitcnt vmcnt(8)
	s_waitcnt lgkmcnt(0)
	s_barrier
	v_mfma_f32_16x16x32_bf16 v[128:131], v[132:135], v[164:167], v[128:131]
	v_mfma_f32_16x16x32_bf16 v[112:115], v[140:143], v[164:167], v[112:115]
	v_mfma_f32_16x16x32_bf16 v[120:123], v[132:135], v[172:175], v[120:123]
	v_mfma_f32_16x16x32_bf16 v[96:99], v[140:143], v[172:175], v[96:99]
	v_mfma_f32_16x16x32_bf16 v[104:107], v[132:135], v[180:183], v[104:107]
	v_mfma_f32_16x16x32_bf16 v[88:91], v[140:143], v[180:183], v[88:91]
	v_mfma_f32_16x16x32_bf16 v[84:87], v[132:135], v[188:191], v[84:87]
	v_mfma_f32_16x16x32_bf16 v[72:75], v[140:143], v[188:191], v[72:75]
	v_mfma_f32_16x16x32_bf16 v[128:131], v[136:139], v[168:171], v[128:131]
	v_mfma_f32_16x16x32_bf16 v[112:115], v[144:147], v[168:171], v[112:115]
	v_mfma_f32_16x16x32_bf16 v[120:123], v[136:139], v[176:179], v[120:123]
	v_mfma_f32_16x16x32_bf16 v[96:99], v[144:147], v[176:179], v[96:99]
	v_mfma_f32_16x16x32_bf16 v[104:107], v[136:139], v[184:187], v[104:107]
	v_mfma_f32_16x16x32_bf16 v[88:91], v[144:147], v[184:187], v[88:91]
	v_mfma_f32_16x16x32_bf16 v[84:87], v[136:139], v[250:253], v[84:87]
	v_mfma_f32_16x16x32_bf16 v[72:75], v[144:147], v[250:253], v[72:75]
	v_mfma_f32_16x16x32_bf16 v[124:127], v[148:151], v[164:167], v[124:127]
	v_mfma_f32_16x16x32_bf16 v[108:111], v[156:159], v[164:167], v[108:111]
	v_mfma_f32_16x16x32_bf16 v[116:119], v[148:151], v[172:175], v[116:119]
	v_mfma_f32_16x16x32_bf16 v[92:95], v[156:159], v[172:175], v[92:95]
	v_mfma_f32_16x16x32_bf16 v[100:103], v[148:151], v[180:183], v[100:103]
	v_mfma_f32_16x16x32_bf16 v[80:83], v[156:159], v[180:183], v[80:83]
	v_mfma_f32_16x16x32_bf16 v[76:79], v[148:151], v[188:191], v[76:79]
	v_mfma_f32_16x16x32_bf16 v[68:71], v[156:159], v[188:191], v[68:71]
	v_mfma_f32_16x16x32_bf16 v[124:127], v[152:155], v[168:171], v[124:127]
	v_mfma_f32_16x16x32_bf16 v[108:111], v[160:163], v[168:171], v[108:111]
	v_mfma_f32_16x16x32_bf16 v[116:119], v[152:155], v[176:179], v[116:119]
	v_mfma_f32_16x16x32_bf16 v[92:95], v[160:163], v[176:179], v[92:95]
	v_mfma_f32_16x16x32_bf16 v[100:103], v[152:155], v[184:187], v[100:103]
	v_mfma_f32_16x16x32_bf16 v[80:83], v[160:163], v[184:187], v[80:83]
	v_mfma_f32_16x16x32_bf16 v[76:79], v[152:155], v[250:253], v[76:79]
	v_mfma_f32_16x16x32_bf16 v[68:71], v[160:163], v[250:253], v[68:71]
	s_barrier
	s_add_i32 s34, s89, s0
	s_mov_b32 m0, s34
	ds_read_b128 v[164:167], v0 offset:16384
	ds_read_b128 v[168:171], v0 offset:17408
	ds_read_b128 v[172:175], v0 offset:18432
	ds_read_b128 v[176:179], v0 offset:19456
	ds_read_b128 v[180:183], v0 offset:20480
	ds_read_b128 v[184:187], v0 offset:21504
	ds_read_b128 v[188:191], v0 offset:22528
	ds_read_b128 v[250:253], v0 offset:23552
	global_load_lds_dwordx4 v196, s[66:67]
	s_add_i32 m0, s34, 0x2000
	s_add_u32 s34, s66, 0x4000
	s_addc_u32 s35, s67, 0
	s_add_i32 s89, vcc_hi, s0
	global_load_lds_dwordx4 v200, s[66:67]
	s_mov_b32 m0, s89
	s_nop 0
	global_load_lds_dwordx4 v196, s[34:35]
	s_add_i32 m0, s89, 0x2000
	s_nop 0
	global_load_lds_dwordx4 v200, s[34:35]
	s_mov_b32 m0, s29
	s_nop 0
	global_load_lds_dwordx4 v198, s[94:95]
	s_mov_b32 m0, s45
	s_nop 0
	global_load_lds_dwordx4 v202, s[94:95]
	s_waitcnt vmcnt(8)
	s_waitcnt lgkmcnt(0)
	s_barrier
	v_mfma_f32_16x16x32_bf16 v[64:67], v[132:135], v[164:167], v[64:67]
	v_mfma_f32_16x16x32_bf16 v[56:59], v[140:143], v[164:167], v[56:59]
	v_mfma_f32_16x16x32_bf16 v[48:51], v[132:135], v[172:175], v[48:51]
	v_mfma_f32_16x16x32_bf16 v[40:43], v[140:143], v[172:175], v[40:43]
	v_mfma_f32_16x16x32_bf16 v[30:33], v[132:135], v[180:183], v[30:33]
	v_mfma_f32_16x16x32_bf16 v[26:29], v[140:143], v[180:183], v[26:29]
	v_mfma_f32_16x16x32_bf16 v[14:17], v[132:135], v[188:191], v[14:17]
	v_mfma_f32_16x16x32_bf16 v[10:13], v[140:143], v[188:191], v[10:13]
	v_mfma_f32_16x16x32_bf16 v[64:67], v[136:139], v[168:171], v[64:67]
	v_mfma_f32_16x16x32_bf16 v[56:59], v[144:147], v[168:171], v[56:59]
	v_mfma_f32_16x16x32_bf16 v[48:51], v[136:139], v[176:179], v[48:51]
	v_mfma_f32_16x16x32_bf16 v[40:43], v[144:147], v[176:179], v[40:43]
	v_mfma_f32_16x16x32_bf16 v[30:33], v[136:139], v[184:187], v[30:33]
	v_mfma_f32_16x16x32_bf16 v[26:29], v[144:147], v[184:187], v[26:29]
	v_mfma_f32_16x16x32_bf16 v[14:17], v[136:139], v[250:253], v[14:17]
	v_mfma_f32_16x16x32_bf16 v[10:13], v[144:147], v[250:253], v[10:13]
	v_mfma_f32_16x16x32_bf16 v[60:63], v[148:151], v[164:167], v[60:63]
	v_mfma_f32_16x16x32_bf16 v[52:55], v[156:159], v[164:167], v[52:55]
	v_mfma_f32_16x16x32_bf16 v[44:47], v[148:151], v[172:175], v[44:47]
	v_mfma_f32_16x16x32_bf16 v[36:39], v[156:159], v[172:175], v[36:39]
	v_mfma_f32_16x16x32_bf16 v[22:25], v[148:151], v[180:183], v[22:25]
	v_mfma_f32_16x16x32_bf16 v[18:21], v[156:159], v[180:183], v[18:21]
	v_mfma_f32_16x16x32_bf16 v[6:9], v[148:151], v[188:191], v[6:9]
	v_mfma_f32_16x16x32_bf16 v[2:5], v[156:159], v[188:191], v[2:5]
	v_mfma_f32_16x16x32_bf16 v[60:63], v[152:155], v[168:171], v[60:63]
	v_mfma_f32_16x16x32_bf16 v[52:55], v[160:163], v[168:171], v[52:55]
	v_mfma_f32_16x16x32_bf16 v[44:47], v[152:155], v[176:179], v[44:47]
	v_mfma_f32_16x16x32_bf16 v[36:39], v[160:163], v[176:179], v[36:39]
	v_mfma_f32_16x16x32_bf16 v[22:25], v[152:155], v[184:187], v[22:25]
	v_mfma_f32_16x16x32_bf16 v[18:21], v[160:163], v[184:187], v[18:21]
	v_mfma_f32_16x16x32_bf16 v[6:9], v[152:155], v[250:253], v[6:9]
	v_mfma_f32_16x16x32_bf16 v[2:5], v[160:163], v[250:253], v[2:5]
	s_barrier
	s_add_i32 s89, 0, 0x18000
	s_add_i32 vcc_hi, 0, 0x1c000
	v_add_u32_e32 v144, s89, v217
	v_add_u32_e32 v160, vcc_hi, v217
	ds_read_b128 v[132:135], v144
	ds_read_b128 v[136:139], v144 offset:1024
	ds_read_b128 v[140:143], v144 offset:2048
	ds_read_b128 v[144:147], v144 offset:3072
	ds_read_b128 v[148:151], v160
	ds_read_b128 v[152:155], v160 offset:1024
	ds_read_b128 v[156:159], v160 offset:2048
	ds_read_b128 v[160:163], v160 offset:3072
	s_add_u32 s34, s94, 0x100000
	s_addc_u32 s35, s95, 0
	s_mov_b32 m0, s82
	ds_read_b128 v[164:167], v0 offset:32768
	ds_read_b128 v[168:171], v0 offset:33792
	ds_read_b128 v[172:175], v0 offset:34816
	ds_read_b128 v[176:179], v0 offset:35840
	ds_read_b128 v[180:183], v0 offset:36864
	ds_read_b128 v[184:187], v0 offset:37888
	ds_read_b128 v[188:191], v0 offset:38912
	ds_read_b128 v[250:253], v0 offset:39936
	global_load_lds_dwordx4 v198, s[34:35]
	s_mov_b32 m0, s90
	s_nop 0
	global_load_lds_dwordx4 v202, s[34:35]
	s_waitcnt vmcnt(8)
	s_waitcnt lgkmcnt(0)
	s_barrier
	v_mfma_f32_16x16x32_bf16 v[128:131], v[132:135], v[164:167], v[128:131]
	v_mfma_f32_16x16x32_bf16 v[112:115], v[140:143], v[164:167], v[112:115]
	v_mfma_f32_16x16x32_bf16 v[120:123], v[132:135], v[172:175], v[120:123]
	v_mfma_f32_16x16x32_bf16 v[96:99], v[140:143], v[172:175], v[96:99]
	v_mfma_f32_16x16x32_bf16 v[104:107], v[132:135], v[180:183], v[104:107]
	v_mfma_f32_16x16x32_bf16 v[88:91], v[140:143], v[180:183], v[88:91]
	v_mfma_f32_16x16x32_bf16 v[84:87], v[132:135], v[188:191], v[84:87]
	v_mfma_f32_16x16x32_bf16 v[72:75], v[140:143], v[188:191], v[72:75]
	v_mfma_f32_16x16x32_bf16 v[128:131], v[136:139], v[168:171], v[128:131]
	v_mfma_f32_16x16x32_bf16 v[112:115], v[144:147], v[168:171], v[112:115]
	v_mfma_f32_16x16x32_bf16 v[120:123], v[136:139], v[176:179], v[120:123]
	v_mfma_f32_16x16x32_bf16 v[96:99], v[144:147], v[176:179], v[96:99]
	v_mfma_f32_16x16x32_bf16 v[104:107], v[136:139], v[184:187], v[104:107]
	v_mfma_f32_16x16x32_bf16 v[88:91], v[144:147], v[184:187], v[88:91]
	v_mfma_f32_16x16x32_bf16 v[84:87], v[136:139], v[250:253], v[84:87]
	v_mfma_f32_16x16x32_bf16 v[72:75], v[144:147], v[250:253], v[72:75]
	v_mfma_f32_16x16x32_bf16 v[124:127], v[148:151], v[164:167], v[124:127]
	v_mfma_f32_16x16x32_bf16 v[108:111], v[156:159], v[164:167], v[108:111]
	v_mfma_f32_16x16x32_bf16 v[116:119], v[148:151], v[172:175], v[116:119]
	v_mfma_f32_16x16x32_bf16 v[92:95], v[156:159], v[172:175], v[92:95]
	v_mfma_f32_16x16x32_bf16 v[100:103], v[148:151], v[180:183], v[100:103]
	v_mfma_f32_16x16x32_bf16 v[80:83], v[156:159], v[180:183], v[80:83]
	v_mfma_f32_16x16x32_bf16 v[76:79], v[148:151], v[188:191], v[76:79]
	v_mfma_f32_16x16x32_bf16 v[68:71], v[156:159], v[188:191], v[68:71]
	v_mfma_f32_16x16x32_bf16 v[124:127], v[152:155], v[168:171], v[124:127]
	v_mfma_f32_16x16x32_bf16 v[108:111], v[160:163], v[168:171], v[108:111]
	v_mfma_f32_16x16x32_bf16 v[116:119], v[152:155], v[176:179], v[116:119]
	v_mfma_f32_16x16x32_bf16 v[92:95], v[160:163], v[176:179], v[92:95]
	v_mfma_f32_16x16x32_bf16 v[100:103], v[152:155], v[184:187], v[100:103]
	v_mfma_f32_16x16x32_bf16 v[80:83], v[160:163], v[184:187], v[80:83]
	v_mfma_f32_16x16x32_bf16 v[76:79], v[152:155], v[250:253], v[76:79]
	v_mfma_f32_16x16x32_bf16 v[68:71], v[160:163], v[250:253], v[68:71]
	s_barrier
	s_add_u32 s34, s66, 0x8000
	s_addc_u32 s35, s67, 0
	s_add_i32 s89, s89, s0
	s_mov_b32 m0, s89
	ds_read_b128 v[164:167], v0 offset:49152
	ds_read_b128 v[168:171], v0 offset:50176
	ds_read_b128 v[172:175], v0 offset:51200
	ds_read_b128 v[176:179], v0 offset:52224
	ds_read_b128 v[180:183], v0 offset:53248
	ds_read_b128 v[184:187], v0 offset:54272
	ds_read_b128 v[188:191], v0 offset:55296
	ds_read_b128 v[250:253], v0 offset:56320
	global_load_lds_dwordx4 v196, s[34:35]
	s_add_i32 m0, s89, 0x2000
	v_lshl_add_u64 v[210:211], s[34:35], 0, v[200:201]
	s_add_u32 s34, s66, 0xc000
	s_addc_u32 s35, s67, 0
	s_add_i32 s66, vcc_hi, s0
	global_load_lds_dwordx4 v[210:211], off
	s_mov_b32 m0, s66
	s_nop 0
	global_load_lds_dwordx4 v196, s[34:35]
	s_add_i32 m0, s66, 0x2000
	s_nop 0
	global_load_lds_dwordx4 v200, s[34:35]
	s_mov_b32 m0, s91
	s_nop 0
	s_add_u32 s100, s94, s92
	s_addc_u32 s101, s95, s93
	global_load_lds_dwordx4 v198, s[100:101]
	s_mov_b32 m0, s30
	s_nop 0
	s_add_u32 s100, s94, s92
	s_addc_u32 s101, s95, s93
	global_load_lds_dwordx4 v202, s[100:101]
	s_waitcnt vmcnt(8)
	s_waitcnt lgkmcnt(0)
	s_barrier
	v_mfma_f32_16x16x32_bf16 v[64:67], v[132:135], v[164:167], v[64:67]
	v_mfma_f32_16x16x32_bf16 v[56:59], v[140:143], v[164:167], v[56:59]
	v_mfma_f32_16x16x32_bf16 v[48:51], v[132:135], v[172:175], v[48:51]
	v_mfma_f32_16x16x32_bf16 v[40:43], v[140:143], v[172:175], v[40:43]
	v_mfma_f32_16x16x32_bf16 v[30:33], v[132:135], v[180:183], v[30:33]
	v_mfma_f32_16x16x32_bf16 v[26:29], v[140:143], v[180:183], v[26:29]
	v_mfma_f32_16x16x32_bf16 v[14:17], v[132:135], v[188:191], v[14:17]
	v_mfma_f32_16x16x32_bf16 v[10:13], v[140:143], v[188:191], v[10:13]
	v_mfma_f32_16x16x32_bf16 v[64:67], v[136:139], v[168:171], v[64:67]
	v_mfma_f32_16x16x32_bf16 v[56:59], v[144:147], v[168:171], v[56:59]
	v_mfma_f32_16x16x32_bf16 v[48:51], v[136:139], v[176:179], v[48:51]
	v_mfma_f32_16x16x32_bf16 v[40:43], v[144:147], v[176:179], v[40:43]
	v_mfma_f32_16x16x32_bf16 v[30:33], v[136:139], v[184:187], v[30:33]
	v_mfma_f32_16x16x32_bf16 v[26:29], v[144:147], v[184:187], v[26:29]
	v_mfma_f32_16x16x32_bf16 v[14:17], v[136:139], v[250:253], v[14:17]
	v_mfma_f32_16x16x32_bf16 v[10:13], v[144:147], v[250:253], v[10:13]
	v_mfma_f32_16x16x32_bf16 v[60:63], v[148:151], v[164:167], v[60:63]
	v_mfma_f32_16x16x32_bf16 v[52:55], v[156:159], v[164:167], v[52:55]
	v_mfma_f32_16x16x32_bf16 v[44:47], v[148:151], v[172:175], v[44:47]
	v_mfma_f32_16x16x32_bf16 v[36:39], v[156:159], v[172:175], v[36:39]
	v_mfma_f32_16x16x32_bf16 v[22:25], v[148:151], v[180:183], v[22:25]
	v_mfma_f32_16x16x32_bf16 v[18:21], v[156:159], v[180:183], v[18:21]
	v_mfma_f32_16x16x32_bf16 v[6:9], v[148:151], v[188:191], v[6:9]
	v_mfma_f32_16x16x32_bf16 v[2:5], v[156:159], v[188:191], v[2:5]
	v_mfma_f32_16x16x32_bf16 v[60:63], v[152:155], v[168:171], v[60:63]
	v_mfma_f32_16x16x32_bf16 v[52:55], v[160:163], v[168:171], v[52:55]
	v_mfma_f32_16x16x32_bf16 v[44:47], v[152:155], v[176:179], v[44:47]
	v_mfma_f32_16x16x32_bf16 v[36:39], v[160:163], v[176:179], v[36:39]
	v_mfma_f32_16x16x32_bf16 v[22:25], v[152:155], v[184:187], v[22:25]
	v_mfma_f32_16x16x32_bf16 v[18:21], v[160:163], v[184:187], v[18:21]
	v_mfma_f32_16x16x32_bf16 v[6:9], v[152:155], v[250:253], v[6:9]
	v_mfma_f32_16x16x32_bf16 v[2:5], v[160:163], v[250:253], v[2:5]
	s_barrier
	s_add_u32 s70, s70, 0x10000
	s_addc_u32 s80, s80, 0
	s_add_u32 s8, s8, 0x100
	s_addc_u32 s9, s9, 0
	s_cmp_lt_i32 vcc_lo, s58
	s_mov_b32 s66, vcc_lo
	s_cbranch_scc1 .LBB0_324
	v_mov_b32_e32 v252, v212
	s_branch .LBB0_235

.LBB0_327:
	s_add_i32 s70, s8, 2
	s_add_u32 s9, s6, 0xfff00080
	s_addc_u32 s10, s7, -1
	s_add_i32 s34, 0, 0x10000
	s_cmp_eq_u32 s59, s8
	s_cselect_b32 s11, s65, s10
	s_cselect_b32 s10, s64, s9
	v_add_u32_e32 v0, s34, v217
	s_cselect_b32 s9, s53, s67
	s_cselect_b32 s8, s52, s66
	s_add_i32 s35, 0, 0x14000
	ds_read_b128 v[132:135], v0
	ds_read_b128 v[136:139], v0 offset:1024
	ds_read_b128 v[140:143], v0 offset:2048
	ds_read_b128 v[144:147], v0 offset:3072
	v_add_u32_e32 v0, s35, v217
	ds_read_b128 v[148:151], v0
	ds_read_b128 v[152:155], v0 offset:1024
	ds_read_b128 v[156:159], v0 offset:2048
	ds_read_b128 v[160:163], v0 offset:3072
	v_add_u32_e32 v0, 0, v216
	s_add_i32 m0, s29, 0xc000
	ds_read_b128 v[164:167], v0
	ds_read_b128 v[168:171], v0 offset:1024
	ds_read_b128 v[172:175], v0 offset:2048
	ds_read_b128 v[176:179], v0 offset:3072
	ds_read_b128 v[180:183], v0 offset:4096
	ds_read_b128 v[184:187], v0 offset:5120
	ds_read_b128 v[188:191], v0 offset:6144
	ds_read_b128 v[250:253], v0 offset:7168
	global_load_lds_dwordx4 v204, s[6:7]
	s_add_i32 m0, s29, 0xe000
	s_nop 0
	global_load_lds_dwordx4 v206, s[6:7]
	s_waitcnt vmcnt(8)
	s_waitcnt lgkmcnt(0)
	s_barrier
	v_mfma_i32_16x16x64_i8 v[128:131], v[132:135], v[164:167], v[128:131]
	v_mfma_i32_16x16x64_i8 v[112:115], v[140:143], v[164:167], v[112:115]
	v_mfma_i32_16x16x64_i8 v[120:123], v[132:135], v[172:175], v[120:123]
	v_mfma_i32_16x16x64_i8 v[96:99], v[140:143], v[172:175], v[96:99]
	v_mfma_i32_16x16x64_i8 v[104:107], v[132:135], v[180:183], v[104:107]
	v_mfma_i32_16x16x64_i8 v[88:91], v[140:143], v[180:183], v[88:91]
	v_mfma_i32_16x16x64_i8 v[84:87], v[132:135], v[188:191], v[84:87]
	v_mfma_i32_16x16x64_i8 v[72:75], v[140:143], v[188:191], v[72:75]
	v_mfma_i32_16x16x64_i8 v[128:131], v[136:139], v[168:171], v[128:131]
	v_mfma_i32_16x16x64_i8 v[112:115], v[144:147], v[168:171], v[112:115]
	v_mfma_i32_16x16x64_i8 v[120:123], v[136:139], v[176:179], v[120:123]
	v_mfma_i32_16x16x64_i8 v[96:99], v[144:147], v[176:179], v[96:99]
	v_mfma_i32_16x16x64_i8 v[104:107], v[136:139], v[184:187], v[104:107]
	v_mfma_i32_16x16x64_i8 v[88:91], v[144:147], v[184:187], v[88:91]
	v_mfma_i32_16x16x64_i8 v[84:87], v[136:139], v[250:253], v[84:87]
	v_mfma_i32_16x16x64_i8 v[72:75], v[144:147], v[250:253], v[72:75]
	v_mfma_i32_16x16x64_i8 v[124:127], v[148:151], v[164:167], v[124:127]
	v_mfma_i32_16x16x64_i8 v[108:111], v[156:159], v[164:167], v[108:111]
	v_mfma_i32_16x16x64_i8 v[116:119], v[148:151], v[172:175], v[116:119]
	v_mfma_i32_16x16x64_i8 v[92:95], v[156:159], v[172:175], v[92:95]
	v_mfma_i32_16x16x64_i8 v[100:103], v[148:151], v[180:183], v[100:103]
	v_mfma_i32_16x16x64_i8 v[80:83], v[156:159], v[180:183], v[80:83]
	v_mfma_i32_16x16x64_i8 v[76:79], v[148:151], v[188:191], v[76:79]
	v_mfma_i32_16x16x64_i8 v[68:71], v[156:159], v[188:191], v[68:71]
	v_mfma_i32_16x16x64_i8 v[124:127], v[152:155], v[168:171], v[124:127]
	v_mfma_i32_16x16x64_i8 v[108:111], v[160:163], v[168:171], v[108:111]
	v_mfma_i32_16x16x64_i8 v[116:119], v[152:155], v[176:179], v[116:119]
	v_mfma_i32_16x16x64_i8 v[92:95], v[160:163], v[176:179], v[92:95]
	v_mfma_i32_16x16x64_i8 v[100:103], v[152:155], v[184:187], v[100:103]
	v_mfma_i32_16x16x64_i8 v[80:83], v[160:163], v[184:187], v[80:83]
	v_mfma_i32_16x16x64_i8 v[76:79], v[152:155], v[250:253], v[76:79]
	v_mfma_i32_16x16x64_i8 v[68:71], v[160:163], v[250:253], v[68:71]
	s_barrier
	s_add_i32 s34, s34, s0
	s_mov_b32 m0, s34
	ds_read_b128 v[164:167], v0 offset:16384
	ds_read_b128 v[168:171], v0 offset:17408
	ds_read_b128 v[172:175], v0 offset:18432
	ds_read_b128 v[176:179], v0 offset:19456
	ds_read_b128 v[180:183], v0 offset:20480
	ds_read_b128 v[184:187], v0 offset:21504
	ds_read_b128 v[188:191], v0 offset:22528
	ds_read_b128 v[250:253], v0 offset:23552
	global_load_lds_dwordx4 v196, s[8:9]
	s_add_i32 m0, s34, 0x2000
	s_add_u32 s94, s8, 0x4000
	s_addc_u32 s95, s9, 0
	s_add_i32 s34, s35, s0
	global_load_lds_dwordx4 v200, s[8:9]
	s_mov_b32 m0, s34
	v_lshl_add_u64 v[194:195], s[10:11], 0, v[202:203]
	global_load_lds_dwordx4 v196, s[94:95]
	s_add_i32 m0, s34, 0x2000
	s_nop 0
	global_load_lds_dwordx4 v200, s[94:95]
	v_lshl_add_u64 v[192:193], s[10:11], 0, v[198:199]
	s_mov_b32 m0, s29
	s_nop 0
	global_load_lds_dwordx4 v198, s[10:11]
	s_mov_b32 m0, s45
	s_nop 0
	global_load_lds_dwordx4 v202, s[10:11]
	s_waitcnt vmcnt(8)
	s_waitcnt lgkmcnt(0)
	s_barrier
	v_mfma_i32_16x16x64_i8 v[64:67], v[132:135], v[164:167], v[64:67]
	v_mfma_i32_16x16x64_i8 v[56:59], v[140:143], v[164:167], v[56:59]
	v_mfma_i32_16x16x64_i8 v[48:51], v[132:135], v[172:175], v[48:51]
	v_mfma_i32_16x16x64_i8 v[40:43], v[140:143], v[172:175], v[40:43]
	v_mfma_i32_16x16x64_i8 v[30:33], v[132:135], v[180:183], v[30:33]
	v_mfma_i32_16x16x64_i8 v[26:29], v[140:143], v[180:183], v[26:29]
	v_mfma_i32_16x16x64_i8 v[14:17], v[132:135], v[188:191], v[14:17]
	v_mfma_i32_16x16x64_i8 v[10:13], v[140:143], v[188:191], v[10:13]
	v_mfma_i32_16x16x64_i8 v[64:67], v[136:139], v[168:171], v[64:67]
	v_mfma_i32_16x16x64_i8 v[56:59], v[144:147], v[168:171], v[56:59]
	v_mfma_i32_16x16x64_i8 v[48:51], v[136:139], v[176:179], v[48:51]
	v_mfma_i32_16x16x64_i8 v[40:43], v[144:147], v[176:179], v[40:43]
	v_mfma_i32_16x16x64_i8 v[30:33], v[136:139], v[184:187], v[30:33]
	v_mfma_i32_16x16x64_i8 v[26:29], v[144:147], v[184:187], v[26:29]
	v_mfma_i32_16x16x64_i8 v[14:17], v[136:139], v[250:253], v[14:17]
	v_mfma_i32_16x16x64_i8 v[10:13], v[144:147], v[250:253], v[10:13]
	v_mfma_i32_16x16x64_i8 v[60:63], v[148:151], v[164:167], v[60:63]
	v_mfma_i32_16x16x64_i8 v[52:55], v[156:159], v[164:167], v[52:55]
	v_mfma_i32_16x16x64_i8 v[44:47], v[148:151], v[172:175], v[44:47]
	v_mfma_i32_16x16x64_i8 v[36:39], v[156:159], v[172:175], v[36:39]
	v_mfma_i32_16x16x64_i8 v[22:25], v[148:151], v[180:183], v[22:25]
	v_mfma_i32_16x16x64_i8 v[18:21], v[156:159], v[180:183], v[18:21]
	v_mfma_i32_16x16x64_i8 v[6:9], v[148:151], v[188:191], v[6:9]
	v_mfma_i32_16x16x64_i8 v[2:5], v[156:159], v[188:191], v[2:5]
	v_mfma_i32_16x16x64_i8 v[60:63], v[152:155], v[168:171], v[60:63]
	v_mfma_i32_16x16x64_i8 v[52:55], v[160:163], v[168:171], v[52:55]
	v_mfma_i32_16x16x64_i8 v[44:47], v[152:155], v[176:179], v[44:47]
	v_mfma_i32_16x16x64_i8 v[36:39], v[160:163], v[176:179], v[36:39]
	v_mfma_i32_16x16x64_i8 v[22:25], v[152:155], v[184:187], v[22:25]
	v_mfma_i32_16x16x64_i8 v[18:21], v[160:163], v[184:187], v[18:21]
	v_mfma_i32_16x16x64_i8 v[6:9], v[152:155], v[250:253], v[6:9]
	v_mfma_i32_16x16x64_i8 v[2:5], v[160:163], v[250:253], v[2:5]
	s_barrier
	s_add_i32 s34, 0, 0x18000
	s_add_i32 s35, 0, 0x1c000
	v_add_u32_e32 v144, s34, v217
	v_add_u32_e32 v160, s35, v217
	ds_read_b128 v[132:135], v144
	ds_read_b128 v[136:139], v144 offset:1024
	ds_read_b128 v[140:143], v144 offset:2048
	ds_read_b128 v[144:147], v144 offset:3072
	ds_read_b128 v[148:151], v160
	ds_read_b128 v[152:155], v160 offset:1024
	ds_read_b128 v[156:159], v160 offset:2048
	ds_read_b128 v[160:163], v160 offset:3072
	s_add_u32 s10, s10, 0x100000
	s_addc_u32 s11, s11, 0
	s_mov_b32 m0, s82
	ds_read_b128 v[164:167], v0 offset:32768
	ds_read_b128 v[168:171], v0 offset:33792
	ds_read_b128 v[172:175], v0 offset:34816
	ds_read_b128 v[176:179], v0 offset:35840
	ds_read_b128 v[180:183], v0 offset:36864
	ds_read_b128 v[184:187], v0 offset:37888
	ds_read_b128 v[188:191], v0 offset:38912
	ds_read_b128 v[250:253], v0 offset:39936
	global_load_lds_dwordx4 v198, s[10:11]
	s_mov_b32 m0, s90
	s_nop 0
	global_load_lds_dwordx4 v202, s[10:11]
	s_waitcnt vmcnt(8)
	s_waitcnt lgkmcnt(0)
	s_barrier
	v_mfma_i32_16x16x64_i8 v[128:131], v[132:135], v[164:167], v[128:131]
	v_mfma_i32_16x16x64_i8 v[112:115], v[140:143], v[164:167], v[112:115]
	v_mfma_i32_16x16x64_i8 v[120:123], v[132:135], v[172:175], v[120:123]
	v_mfma_i32_16x16x64_i8 v[96:99], v[140:143], v[172:175], v[96:99]
	v_mfma_i32_16x16x64_i8 v[104:107], v[132:135], v[180:183], v[104:107]
	v_mfma_i32_16x16x64_i8 v[88:91], v[140:143], v[180:183], v[88:91]
	v_mfma_i32_16x16x64_i8 v[84:87], v[132:135], v[188:191], v[84:87]
	v_mfma_i32_16x16x64_i8 v[72:75], v[140:143], v[188:191], v[72:75]
	v_mfma_i32_16x16x64_i8 v[128:131], v[136:139], v[168:171], v[128:131]
	v_mfma_i32_16x16x64_i8 v[112:115], v[144:147], v[168:171], v[112:115]
	v_mfma_i32_16x16x64_i8 v[120:123], v[136:139], v[176:179], v[120:123]
	v_mfma_i32_16x16x64_i8 v[96:99], v[144:147], v[176:179], v[96:99]
	v_mfma_i32_16x16x64_i8 v[104:107], v[136:139], v[184:187], v[104:107]
	v_mfma_i32_16x16x64_i8 v[88:91], v[144:147], v[184:187], v[88:91]
	v_mfma_i32_16x16x64_i8 v[84:87], v[136:139], v[250:253], v[84:87]
	v_mfma_i32_16x16x64_i8 v[72:75], v[144:147], v[250:253], v[72:75]
	v_mfma_i32_16x16x64_i8 v[124:127], v[148:151], v[164:167], v[124:127]
	v_mfma_i32_16x16x64_i8 v[108:111], v[156:159], v[164:167], v[108:111]
	v_mfma_i32_16x16x64_i8 v[116:119], v[148:151], v[172:175], v[116:119]
	v_mfma_i32_16x16x64_i8 v[92:95], v[156:159], v[172:175], v[92:95]
	v_mfma_i32_16x16x64_i8 v[100:103], v[148:151], v[180:183], v[100:103]
	v_mfma_i32_16x16x64_i8 v[80:83], v[156:159], v[180:183], v[80:83]
	v_mfma_i32_16x16x64_i8 v[76:79], v[148:151], v[188:191], v[76:79]
	v_mfma_i32_16x16x64_i8 v[68:71], v[156:159], v[188:191], v[68:71]
	v_mfma_i32_16x16x64_i8 v[124:127], v[152:155], v[168:171], v[124:127]
	v_mfma_i32_16x16x64_i8 v[108:111], v[160:163], v[168:171], v[108:111]
	v_mfma_i32_16x16x64_i8 v[116:119], v[152:155], v[176:179], v[116:119]
	v_mfma_i32_16x16x64_i8 v[92:95], v[160:163], v[176:179], v[92:95]
	v_mfma_i32_16x16x64_i8 v[100:103], v[152:155], v[184:187], v[100:103]
	v_mfma_i32_16x16x64_i8 v[80:83], v[160:163], v[184:187], v[80:83]
	v_mfma_i32_16x16x64_i8 v[76:79], v[152:155], v[250:253], v[76:79]
	v_mfma_i32_16x16x64_i8 v[68:71], v[160:163], v[250:253], v[68:71]
	s_barrier
	s_add_u32 s10, s8, 0x8000
	s_addc_u32 s11, s9, 0
	s_add_i32 s34, s34, s0
	s_mov_b32 m0, s34
	ds_read_b128 v[164:167], v0 offset:49152
	ds_read_b128 v[168:171], v0 offset:50176
	ds_read_b128 v[172:175], v0 offset:51200
	ds_read_b128 v[176:179], v0 offset:52224
	ds_read_b128 v[180:183], v0 offset:53248
	ds_read_b128 v[184:187], v0 offset:54272
	ds_read_b128 v[188:191], v0 offset:55296
	ds_read_b128 v[250:253], v0 offset:56320
	global_load_lds_dwordx4 v196, s[10:11]
	s_add_i32 m0, s34, 0x2000
	s_add_u32 s8, s8, 0xc000
	v_lshl_add_u64 v[210:211], s[10:11], 0, v[200:201]
	s_addc_u32 s9, s9, 0
	s_add_i32 s10, s35, s0
	global_load_lds_dwordx4 v[210:211], off
	s_mov_b32 m0, s10
	v_lshl_add_u64 v[192:193], v[192:193], 0, s[92:93]
	global_load_lds_dwordx4 v196, s[8:9]
	s_add_i32 m0, s10, 0x2000
	s_nop 0
	global_load_lds_dwordx4 v200, s[8:9]
	s_mov_b32 m0, s91
	s_nop 0
	global_load_lds_dwordx4 v[192:193], off
	v_lshl_add_u64 v[192:193], v[194:195], 0, s[92:93]
	s_mov_b32 m0, s30
	s_nop 0
	global_load_lds_dwordx4 v[192:193], off
	s_waitcnt vmcnt(8)
	s_waitcnt lgkmcnt(0)
	s_barrier
	v_mfma_i32_16x16x64_i8 v[64:67], v[132:135], v[164:167], v[64:67]
	v_mfma_i32_16x16x64_i8 v[56:59], v[140:143], v[164:167], v[56:59]
	v_mfma_i32_16x16x64_i8 v[48:51], v[132:135], v[172:175], v[48:51]
	v_mfma_i32_16x16x64_i8 v[40:43], v[140:143], v[172:175], v[40:43]
	v_mfma_i32_16x16x64_i8 v[30:33], v[132:135], v[180:183], v[30:33]
	v_mfma_i32_16x16x64_i8 v[26:29], v[140:143], v[180:183], v[26:29]
	v_mfma_i32_16x16x64_i8 v[14:17], v[132:135], v[188:191], v[14:17]
	v_mfma_i32_16x16x64_i8 v[10:13], v[140:143], v[188:191], v[10:13]
	v_mfma_i32_16x16x64_i8 v[64:67], v[136:139], v[168:171], v[64:67]
	v_mfma_i32_16x16x64_i8 v[56:59], v[144:147], v[168:171], v[56:59]
	v_mfma_i32_16x16x64_i8 v[48:51], v[136:139], v[176:179], v[48:51]
	v_mfma_i32_16x16x64_i8 v[40:43], v[144:147], v[176:179], v[40:43]
	v_mfma_i32_16x16x64_i8 v[30:33], v[136:139], v[184:187], v[30:33]
	v_mfma_i32_16x16x64_i8 v[26:29], v[144:147], v[184:187], v[26:29]
	v_mfma_i32_16x16x64_i8 v[14:17], v[136:139], v[250:253], v[14:17]
	v_mfma_i32_16x16x64_i8 v[10:13], v[144:147], v[250:253], v[10:13]
	v_mfma_i32_16x16x64_i8 v[60:63], v[148:151], v[164:167], v[60:63]
	v_mfma_i32_16x16x64_i8 v[52:55], v[156:159], v[164:167], v[52:55]
	v_mfma_i32_16x16x64_i8 v[44:47], v[148:151], v[172:175], v[44:47]
	v_mfma_i32_16x16x64_i8 v[36:39], v[156:159], v[172:175], v[36:39]
	v_mfma_i32_16x16x64_i8 v[22:25], v[148:151], v[180:183], v[22:25]
	v_mfma_i32_16x16x64_i8 v[18:21], v[156:159], v[180:183], v[18:21]
	v_mfma_i32_16x16x64_i8 v[6:9], v[148:151], v[188:191], v[6:9]
	v_mfma_i32_16x16x64_i8 v[2:5], v[156:159], v[188:191], v[2:5]
	v_mfma_i32_16x16x64_i8 v[60:63], v[152:155], v[168:171], v[60:63]
	v_mfma_i32_16x16x64_i8 v[52:55], v[160:163], v[168:171], v[52:55]
	v_mfma_i32_16x16x64_i8 v[44:47], v[152:155], v[176:179], v[44:47]
	v_mfma_i32_16x16x64_i8 v[36:39], v[160:163], v[176:179], v[36:39]
	v_mfma_i32_16x16x64_i8 v[22:25], v[152:155], v[184:187], v[22:25]
	v_mfma_i32_16x16x64_i8 v[18:21], v[160:163], v[184:187], v[18:21]
	v_mfma_i32_16x16x64_i8 v[6:9], v[152:155], v[250:253], v[6:9]
	v_mfma_i32_16x16x64_i8 v[2:5], v[160:163], v[250:253], v[2:5]
	s_barrier
	s_add_u32 s66, s66, 0x10000
	s_addc_u32 s67, s67, 0
	s_add_u32 s6, s6, 0x100
	s_addc_u32 s7, s7, 0
	s_cmp_ge_i32 s70, s58
	s_mov_b32 s8, s70
	s_cbranch_scc0 .LBB0_327
	v_mov_b32_e32 v252, v212
	v_cndmask_b32_e64 v0, 0, 1, s[46:47]
	v_cmp_ne_u32_e64 s[6:7], 1, v0
	s_andn2_b64 vcc, exec, s[46:47]
	s_cbranch_vccz .LBB0_236
	s_branch .LBB0_237

.LBB0_707:
	s_add_u32 s34, s50, 0xfff80080
	s_addc_u32 s35, s51, -1
	s_add_i32 s61, 0, 0x10000
	s_cmp_eq_u32 s60, 4
	s_cselect_b32 s55, s23, s35
	s_cselect_b32 s54, s22, s34
	v_add_u32_e32 v0, s61, v202
	s_cselect_b32 s53, s43, s59
	s_cselect_b32 s52, s42, s21
	s_add_i32 s62, 0, 0x14000
	ds_read_b128 v[164:167], v0
	ds_read_b128 v[168:171], v0 offset:1024
	ds_read_b128 v[172:175], v0 offset:2048
	ds_read_b128 v[176:179], v0 offset:3072
	v_add_u32_e32 v0, s62, v202
	ds_read_b128 v[192:195], v0
	ds_read_b128 v[196:199], v0 offset:1024
	ds_read_b128 v[204:207], v0 offset:2048
	ds_read_b128 v[210:213], v0 offset:3072
	s_add_i32 m0, s29, 0xc000
	ds_read_b128 v[216:219], v203
	ds_read_b128 v[220:223], v203 offset:1024
	ds_read_b128 v[224:227], v203 offset:2048
	ds_read_b128 v[228:231], v203 offset:3072
	ds_read_b128 v[232:235], v203 offset:4096
	ds_read_b128 v[236:239], v203 offset:5120
	ds_read_b128 v[240:243], v203 offset:6144
	ds_read_b128 v[244:247], v203 offset:7168
	global_load_lds_dwordx4 v188, s[50:51]
	s_add_i32 m0, s29, 0xe000
	s_nop 0
	global_load_lds_dwordx4 v190, s[50:51]
	s_waitcnt vmcnt(8)
	s_waitcnt lgkmcnt(0)
	s_barrier
	v_mfma_f32_16x16x32_bf16 v[160:163], v[164:167], v[216:219], v[160:163]
	v_mfma_f32_16x16x32_bf16 v[156:159], v[172:175], v[216:219], v[156:159]
	v_mfma_f32_16x16x32_bf16 v[144:147], v[164:167], v[224:227], v[144:147]
	v_mfma_f32_16x16x32_bf16 v[140:143], v[172:175], v[224:227], v[140:143]
	v_mfma_f32_16x16x32_bf16 v[128:131], v[164:167], v[232:235], v[128:131]
	v_mfma_f32_16x16x32_bf16 v[124:127], v[172:175], v[232:235], v[124:127]
	v_mfma_f32_16x16x32_bf16 v[112:115], v[164:167], v[240:243], v[112:115]
	v_mfma_f32_16x16x32_bf16 v[108:111], v[172:175], v[240:243], v[108:111]
	v_mfma_f32_16x16x32_bf16 v[160:163], v[168:171], v[220:223], v[160:163]
	v_mfma_f32_16x16x32_bf16 v[156:159], v[176:179], v[220:223], v[156:159]
	v_mfma_f32_16x16x32_bf16 v[144:147], v[168:171], v[228:231], v[144:147]
	v_mfma_f32_16x16x32_bf16 v[140:143], v[176:179], v[228:231], v[140:143]
	v_mfma_f32_16x16x32_bf16 v[128:131], v[168:171], v[236:239], v[128:131]
	v_mfma_f32_16x16x32_bf16 v[124:127], v[176:179], v[236:239], v[124:127]
	v_mfma_f32_16x16x32_bf16 v[112:115], v[168:171], v[244:247], v[112:115]
	v_mfma_f32_16x16x32_bf16 v[108:111], v[176:179], v[244:247], v[108:111]
	v_mfma_f32_16x16x32_bf16 v[152:155], v[192:195], v[216:219], v[152:155]
	v_mfma_f32_16x16x32_bf16 v[148:151], v[204:207], v[216:219], v[148:151]
	v_mfma_f32_16x16x32_bf16 v[136:139], v[192:195], v[224:227], v[136:139]
	v_mfma_f32_16x16x32_bf16 v[132:135], v[204:207], v[224:227], v[132:135]
	v_mfma_f32_16x16x32_bf16 v[120:123], v[192:195], v[232:235], v[120:123]
	v_mfma_f32_16x16x32_bf16 v[116:119], v[204:207], v[232:235], v[116:119]
	v_mfma_f32_16x16x32_bf16 v[104:107], v[192:195], v[240:243], v[104:107]
	v_mfma_f32_16x16x32_bf16 v[100:103], v[204:207], v[240:243], v[100:103]
	v_mfma_f32_16x16x32_bf16 v[152:155], v[196:199], v[220:223], v[152:155]
	v_mfma_f32_16x16x32_bf16 v[148:151], v[210:213], v[220:223], v[148:151]
	v_mfma_f32_16x16x32_bf16 v[136:139], v[196:199], v[228:231], v[136:139]
	v_mfma_f32_16x16x32_bf16 v[132:135], v[210:213], v[228:231], v[132:135]
	v_mfma_f32_16x16x32_bf16 v[120:123], v[196:199], v[236:239], v[120:123]
	v_mfma_f32_16x16x32_bf16 v[116:119], v[210:213], v[236:239], v[116:119]
	v_mfma_f32_16x16x32_bf16 v[104:107], v[196:199], v[244:247], v[104:107]
	v_mfma_f32_16x16x32_bf16 v[100:103], v[210:213], v[244:247], v[100:103]
	s_barrier
	s_add_i32 s34, s61, s0
	s_mov_b32 m0, s34
	ds_read_b128 v[216:219], v203 offset:16384
	ds_read_b128 v[220:223], v203 offset:17408
	ds_read_b128 v[224:227], v203 offset:18432
	ds_read_b128 v[228:231], v203 offset:19456
	ds_read_b128 v[232:235], v203 offset:20480
	ds_read_b128 v[236:239], v203 offset:21504
	ds_read_b128 v[240:243], v203 offset:22528
	ds_read_b128 v[244:247], v203 offset:23552
	global_load_lds_dwordx4 v180, s[52:53]
	s_add_i32 m0, s34, 0x2000
	s_add_u32 s34, s52, 0x4000
	s_addc_u32 s35, s53, 0
	s_add_i32 s61, s62, s0
	global_load_lds_dwordx4 v184, s[52:53]
	s_mov_b32 m0, s61
	v_lshl_add_u64 v[248:249], s[54:55], 0, v[186:187]
	global_load_lds_dwordx4 v180, s[34:35]
	s_add_i32 m0, s61, 0x2000
	s_nop 0
	global_load_lds_dwordx4 v184, s[34:35]
	v_lshl_add_u64 v[200:201], s[54:55], 0, v[182:183]
	s_mov_b32 m0, s29
	s_nop 0
	global_load_lds_dwordx4 v182, s[54:55]
	s_mov_b32 m0, s45
	s_nop 0
	global_load_lds_dwordx4 v186, s[54:55]
	s_waitcnt vmcnt(8)
	s_waitcnt lgkmcnt(0)
	s_barrier
	v_mfma_f32_16x16x32_bf16 v[96:99], v[164:167], v[216:219], v[96:99]
	v_mfma_f32_16x16x32_bf16 v[92:95], v[172:175], v[216:219], v[92:95]
	v_mfma_f32_16x16x32_bf16 v[84:87], v[164:167], v[224:227], v[84:87]
	v_mfma_f32_16x16x32_bf16 v[76:79], v[172:175], v[224:227], v[76:79]
	v_mfma_f32_16x16x32_bf16 v[68:71], v[164:167], v[232:235], v[68:71]
	v_mfma_f32_16x16x32_bf16 v[60:63], v[172:175], v[232:235], v[60:63]
	v_mfma_f32_16x16x32_bf16 v[52:55], v[164:167], v[240:243], v[52:55]
	v_mfma_f32_16x16x32_bf16 v[44:47], v[172:175], v[240:243], v[44:47]
	v_mfma_f32_16x16x32_bf16 v[96:99], v[168:171], v[220:223], v[96:99]
	v_mfma_f32_16x16x32_bf16 v[92:95], v[176:179], v[220:223], v[92:95]
	v_mfma_f32_16x16x32_bf16 v[84:87], v[168:171], v[228:231], v[84:87]
	v_mfma_f32_16x16x32_bf16 v[76:79], v[176:179], v[228:231], v[76:79]
	v_mfma_f32_16x16x32_bf16 v[68:71], v[168:171], v[236:239], v[68:71]
	v_mfma_f32_16x16x32_bf16 v[60:63], v[176:179], v[236:239], v[60:63]
	v_mfma_f32_16x16x32_bf16 v[52:55], v[168:171], v[244:247], v[52:55]
	v_mfma_f32_16x16x32_bf16 v[44:47], v[176:179], v[244:247], v[44:47]
	v_mfma_f32_16x16x32_bf16 v[88:91], v[192:195], v[216:219], v[88:91]
	v_mfma_f32_16x16x32_bf16 v[80:83], v[204:207], v[216:219], v[80:83]
	v_mfma_f32_16x16x32_bf16 v[72:75], v[192:195], v[224:227], v[72:75]
	v_mfma_f32_16x16x32_bf16 v[64:67], v[204:207], v[224:227], v[64:67]
	v_mfma_f32_16x16x32_bf16 v[56:59], v[192:195], v[232:235], v[56:59]
	v_mfma_f32_16x16x32_bf16 v[48:51], v[204:207], v[232:235], v[48:51]
	v_mfma_f32_16x16x32_bf16 v[40:43], v[192:195], v[240:243], v[40:43]
	v_mfma_f32_16x16x32_bf16 v[36:39], v[204:207], v[240:243], v[36:39]
	v_mfma_f32_16x16x32_bf16 v[88:91], v[196:199], v[220:223], v[88:91]
	v_mfma_f32_16x16x32_bf16 v[80:83], v[210:213], v[220:223], v[80:83]
	v_mfma_f32_16x16x32_bf16 v[72:75], v[196:199], v[228:231], v[72:75]
	v_mfma_f32_16x16x32_bf16 v[64:67], v[210:213], v[228:231], v[64:67]
	v_mfma_f32_16x16x32_bf16 v[56:59], v[196:199], v[236:239], v[56:59]
	v_mfma_f32_16x16x32_bf16 v[48:51], v[210:213], v[236:239], v[48:51]
	v_mfma_f32_16x16x32_bf16 v[40:43], v[196:199], v[244:247], v[40:43]
	v_mfma_f32_16x16x32_bf16 v[36:39], v[210:213], v[244:247], v[36:39]
	s_barrier
	s_add_i32 s61, 0, 0x18000
	v_add_u32_e32 v0, s61, v202
	s_add_i32 s62, 0, 0x1c000
	ds_read_b128 v[164:167], v0
	ds_read_b128 v[168:171], v0 offset:1024
	ds_read_b128 v[172:175], v0 offset:2048
	ds_read_b128 v[176:179], v0 offset:3072
	v_add_u32_e32 v0, s62, v202
	ds_read_b128 v[192:195], v0
	ds_read_b128 v[196:199], v0 offset:1024
	ds_read_b128 v[204:207], v0 offset:2048
	ds_read_b128 v[210:213], v0 offset:3072
	s_add_u32 s34, s54, 0x80000
	s_addc_u32 s35, s55, 0
	s_mov_b32 m0, s82
	ds_read_b128 v[216:219], v203 offset:32768
	ds_read_b128 v[220:223], v203 offset:33792
	ds_read_b128 v[224:227], v203 offset:34816
	ds_read_b128 v[228:231], v203 offset:35840
	ds_read_b128 v[232:235], v203 offset:36864
	ds_read_b128 v[236:239], v203 offset:37888
	ds_read_b128 v[240:243], v203 offset:38912
	ds_read_b128 v[244:247], v203 offset:39936
	global_load_lds_dwordx4 v182, s[34:35]
	s_mov_b32 m0, s90
	s_nop 0
	global_load_lds_dwordx4 v186, s[34:35]
	s_waitcnt vmcnt(8)
	s_waitcnt lgkmcnt(0)
	s_barrier
	v_mfma_f32_16x16x32_bf16 v[160:163], v[164:167], v[216:219], v[160:163]
	v_mfma_f32_16x16x32_bf16 v[156:159], v[172:175], v[216:219], v[156:159]
	v_mfma_f32_16x16x32_bf16 v[144:147], v[164:167], v[224:227], v[144:147]
	v_mfma_f32_16x16x32_bf16 v[140:143], v[172:175], v[224:227], v[140:143]
	v_mfma_f32_16x16x32_bf16 v[128:131], v[164:167], v[232:235], v[128:131]
	v_mfma_f32_16x16x32_bf16 v[124:127], v[172:175], v[232:235], v[124:127]
	v_mfma_f32_16x16x32_bf16 v[112:115], v[164:167], v[240:243], v[112:115]
	v_mfma_f32_16x16x32_bf16 v[108:111], v[172:175], v[240:243], v[108:111]
	v_mfma_f32_16x16x32_bf16 v[160:163], v[168:171], v[220:223], v[160:163]
	v_mfma_f32_16x16x32_bf16 v[156:159], v[176:179], v[220:223], v[156:159]
	v_mfma_f32_16x16x32_bf16 v[144:147], v[168:171], v[228:231], v[144:147]
	v_mfma_f32_16x16x32_bf16 v[140:143], v[176:179], v[228:231], v[140:143]
	v_mfma_f32_16x16x32_bf16 v[128:131], v[168:171], v[236:239], v[128:131]
	v_mfma_f32_16x16x32_bf16 v[124:127], v[176:179], v[236:239], v[124:127]
	v_mfma_f32_16x16x32_bf16 v[112:115], v[168:171], v[244:247], v[112:115]
	v_mfma_f32_16x16x32_bf16 v[108:111], v[176:179], v[244:247], v[108:111]
	v_mfma_f32_16x16x32_bf16 v[152:155], v[192:195], v[216:219], v[152:155]
	v_mfma_f32_16x16x32_bf16 v[148:151], v[204:207], v[216:219], v[148:151]
	v_mfma_f32_16x16x32_bf16 v[136:139], v[192:195], v[224:227], v[136:139]
	v_mfma_f32_16x16x32_bf16 v[132:135], v[204:207], v[224:227], v[132:135]
	v_mfma_f32_16x16x32_bf16 v[120:123], v[192:195], v[232:235], v[120:123]
	v_mfma_f32_16x16x32_bf16 v[116:119], v[204:207], v[232:235], v[116:119]
	v_mfma_f32_16x16x32_bf16 v[104:107], v[192:195], v[240:243], v[104:107]
	v_mfma_f32_16x16x32_bf16 v[100:103], v[204:207], v[240:243], v[100:103]
	v_mfma_f32_16x16x32_bf16 v[152:155], v[196:199], v[220:223], v[152:155]
	v_mfma_f32_16x16x32_bf16 v[148:151], v[210:213], v[220:223], v[148:151]
	v_mfma_f32_16x16x32_bf16 v[136:139], v[196:199], v[228:231], v[136:139]
	v_mfma_f32_16x16x32_bf16 v[132:135], v[210:213], v[228:231], v[132:135]
	v_mfma_f32_16x16x32_bf16 v[120:123], v[196:199], v[236:239], v[120:123]
	v_mfma_f32_16x16x32_bf16 v[116:119], v[210:213], v[236:239], v[116:119]
	v_mfma_f32_16x16x32_bf16 v[104:107], v[196:199], v[244:247], v[104:107]
	v_mfma_f32_16x16x32_bf16 v[100:103], v[210:213], v[244:247], v[100:103]
	s_barrier
	s_add_u32 s34, s52, 0x8000
	s_addc_u32 s35, s53, 0
	s_add_i32 s54, s61, s0
	s_mov_b32 m0, s54
	ds_read_b128 v[216:219], v203 offset:49152
	ds_read_b128 v[220:223], v203 offset:50176
	ds_read_b128 v[224:227], v203 offset:51200
	ds_read_b128 v[228:231], v203 offset:52224
	ds_read_b128 v[232:235], v203 offset:53248
	ds_read_b128 v[236:239], v203 offset:54272
	ds_read_b128 v[240:243], v203 offset:55296
	ds_read_b128 v[244:247], v203 offset:56320
	global_load_lds_dwordx4 v180, s[34:35]
	s_add_i32 m0, s54, 0x2000
	v_lshl_add_u64 v[250:251], s[34:35], 0, v[184:185]
	s_add_u32 s34, s52, 0xc000
	s_addc_u32 s35, s53, 0
	s_add_i32 s52, s62, s0
	global_load_lds_dwordx4 v[250:251], off
	s_mov_b32 m0, s52
	v_lshl_add_u64 v[200:201], v[200:201], 0, s[92:93]
	global_load_lds_dwordx4 v180, s[34:35]
	s_add_i32 m0, s52, 0x2000
	s_nop 0
	global_load_lds_dwordx4 v184, s[34:35]
	s_mov_b32 m0, s91
	s_nop 0
	global_load_lds_dwordx4 v[200:201], off
	v_lshl_add_u64 v[200:201], v[248:249], 0, s[92:93]
	s_mov_b32 m0, s30
	s_nop 0
	global_load_lds_dwordx4 v[200:201], off
	s_waitcnt vmcnt(8)
	s_waitcnt lgkmcnt(0)
	s_barrier
	v_mfma_f32_16x16x32_bf16 v[96:99], v[164:167], v[216:219], v[96:99]
	v_mfma_f32_16x16x32_bf16 v[92:95], v[172:175], v[216:219], v[92:95]
	v_mfma_f32_16x16x32_bf16 v[84:87], v[164:167], v[224:227], v[84:87]
	v_mfma_f32_16x16x32_bf16 v[76:79], v[172:175], v[224:227], v[76:79]
	v_mfma_f32_16x16x32_bf16 v[68:71], v[164:167], v[232:235], v[68:71]
	v_mfma_f32_16x16x32_bf16 v[60:63], v[172:175], v[232:235], v[60:63]
	v_mfma_f32_16x16x32_bf16 v[52:55], v[164:167], v[240:243], v[52:55]
	v_mfma_f32_16x16x32_bf16 v[44:47], v[172:175], v[240:243], v[44:47]
	v_mfma_f32_16x16x32_bf16 v[96:99], v[168:171], v[220:223], v[96:99]
	v_mfma_f32_16x16x32_bf16 v[92:95], v[176:179], v[220:223], v[92:95]
	v_mfma_f32_16x16x32_bf16 v[84:87], v[168:171], v[228:231], v[84:87]
	v_mfma_f32_16x16x32_bf16 v[76:79], v[176:179], v[228:231], v[76:79]
	v_mfma_f32_16x16x32_bf16 v[68:71], v[168:171], v[236:239], v[68:71]
	v_mfma_f32_16x16x32_bf16 v[60:63], v[176:179], v[236:239], v[60:63]
	v_mfma_f32_16x16x32_bf16 v[52:55], v[168:171], v[244:247], v[52:55]
	v_mfma_f32_16x16x32_bf16 v[44:47], v[176:179], v[244:247], v[44:47]
	v_mfma_f32_16x16x32_bf16 v[88:91], v[192:195], v[216:219], v[88:91]
	v_mfma_f32_16x16x32_bf16 v[80:83], v[204:207], v[216:219], v[80:83]
	v_mfma_f32_16x16x32_bf16 v[72:75], v[192:195], v[224:227], v[72:75]
	v_mfma_f32_16x16x32_bf16 v[64:67], v[204:207], v[224:227], v[64:67]
	v_mfma_f32_16x16x32_bf16 v[56:59], v[192:195], v[232:235], v[56:59]
	v_mfma_f32_16x16x32_bf16 v[48:51], v[204:207], v[232:235], v[48:51]
	v_mfma_f32_16x16x32_bf16 v[40:43], v[192:195], v[240:243], v[40:43]
	v_mfma_f32_16x16x32_bf16 v[36:39], v[204:207], v[240:243], v[36:39]
	v_mfma_f32_16x16x32_bf16 v[88:91], v[196:199], v[220:223], v[88:91]
	v_mfma_f32_16x16x32_bf16 v[80:83], v[210:213], v[220:223], v[80:83]
	v_mfma_f32_16x16x32_bf16 v[72:75], v[196:199], v[228:231], v[72:75]
	v_mfma_f32_16x16x32_bf16 v[64:67], v[210:213], v[228:231], v[64:67]
	v_mfma_f32_16x16x32_bf16 v[56:59], v[196:199], v[236:239], v[56:59]
	v_mfma_f32_16x16x32_bf16 v[48:51], v[210:213], v[236:239], v[48:51]
	v_mfma_f32_16x16x32_bf16 v[40:43], v[196:199], v[244:247], v[40:43]
	v_mfma_f32_16x16x32_bf16 v[36:39], v[210:213], v[244:247], v[36:39]
	s_barrier
	s_add_i32 s60, s60, 2
	s_add_u32 s21, s21, 0x10000
	s_addc_u32 s59, s59, 0
	s_add_u32 s50, s50, 0x100
	s_addc_u32 s51, s51, 0
	s_cmp_gt_u32 s60, 5
	s_cbranch_scc0 .LBB0_707
	s_and_b64 vcc, exec, s[46:47]
	s_cbranch_vccz .LBB0_710
	s_barrier

.LBB0_788:
	s_add_u32 s34, s48, 0xfff80080
	s_addc_u32 s35, s49, -1
	s_add_i32 s57, 0, 0x10000
	s_cmp_eq_u32 s56, 28
	s_cselect_b32 s55, s23, s35
	s_cselect_b32 s54, s22, s34
	v_add_u32_e32 v0, s57, v198
	s_cselect_b32 s53, s43, s51
	s_cselect_b32 s52, s42, s15
	s_add_i32 s69, 0, 0x14000
	ds_read_b128 v[136:139], v0
	ds_read_b128 v[140:143], v0 offset:1024
	ds_read_b128 v[144:147], v0 offset:2048
	ds_read_b128 v[148:151], v0 offset:3072
	v_add_u32_e32 v0, s69, v198
	ds_read_b128 v[152:155], v0
	ds_read_b128 v[156:159], v0 offset:1024
	ds_read_b128 v[160:163], v0 offset:2048
	ds_read_b128 v[174:177], v0 offset:3072
	s_add_i32 m0, s29, 0xc000
	ds_read_b128 v[178:181], v199
	ds_read_b128 v[182:185], v199 offset:1024
	ds_read_b128 v[186:189], v199 offset:2048
	ds_read_b128 v[190:193], v199 offset:3072
	ds_read_b128 v[194:197], v199 offset:4096
	ds_read_b128 v[210:213], v199 offset:5120
	ds_read_b128 v[240:243], v199 offset:6144
	ds_read_b128 v[244:247], v199 offset:7168
	global_load_lds_dwordx4 v170, s[48:49]
	s_add_i32 m0, s29, 0xe000
	s_nop 0
	global_load_lds_dwordx4 v172, s[48:49]
	s_waitcnt vmcnt(8)
	s_waitcnt lgkmcnt(0)
	s_barrier
	v_mfma_f32_16x16x32_bf16 v[132:135], v[136:139], v[178:181], v[132:135]
	v_mfma_f32_16x16x32_bf16 v[128:131], v[144:147], v[178:181], v[128:131]
	v_mfma_f32_16x16x32_bf16 v[124:127], v[136:139], v[186:189], v[124:127]
	v_mfma_f32_16x16x32_bf16 v[120:123], v[144:147], v[186:189], v[120:123]
	v_mfma_f32_16x16x32_bf16 v[116:119], v[136:139], v[194:197], v[116:119]
	v_mfma_f32_16x16x32_bf16 v[112:115], v[144:147], v[194:197], v[112:115]
	v_mfma_f32_16x16x32_bf16 v[108:111], v[136:139], v[240:243], v[108:111]
	v_mfma_f32_16x16x32_bf16 v[104:107], v[144:147], v[240:243], v[104:107]
	v_mfma_f32_16x16x32_bf16 v[132:135], v[140:143], v[182:185], v[132:135]
	v_mfma_f32_16x16x32_bf16 v[128:131], v[148:151], v[182:185], v[128:131]
	v_mfma_f32_16x16x32_bf16 v[124:127], v[140:143], v[190:193], v[124:127]
	v_mfma_f32_16x16x32_bf16 v[120:123], v[148:151], v[190:193], v[120:123]
	v_mfma_f32_16x16x32_bf16 v[116:119], v[140:143], v[210:213], v[116:119]
	v_mfma_f32_16x16x32_bf16 v[112:115], v[148:151], v[210:213], v[112:115]
	v_mfma_f32_16x16x32_bf16 v[108:111], v[140:143], v[244:247], v[108:111]
	v_mfma_f32_16x16x32_bf16 v[104:107], v[148:151], v[244:247], v[104:107]
	v_mfma_f32_16x16x32_bf16 v[100:103], v[152:155], v[178:181], v[100:103]
	v_mfma_f32_16x16x32_bf16 v[96:99], v[160:163], v[178:181], v[96:99]
	v_mfma_f32_16x16x32_bf16 v[92:95], v[152:155], v[186:189], v[92:95]
	v_mfma_f32_16x16x32_bf16 v[88:91], v[160:163], v[186:189], v[88:91]
	v_mfma_f32_16x16x32_bf16 v[84:87], v[152:155], v[194:197], v[84:87]
	v_mfma_f32_16x16x32_bf16 v[80:83], v[160:163], v[194:197], v[80:83]
	v_mfma_f32_16x16x32_bf16 v[72:75], v[152:155], v[240:243], v[72:75]
	v_mfma_f32_16x16x32_bf16 v[64:67], v[160:163], v[240:243], v[64:67]
	v_mfma_f32_16x16x32_bf16 v[100:103], v[156:159], v[182:185], v[100:103]
	v_mfma_f32_16x16x32_bf16 v[96:99], v[174:177], v[182:185], v[96:99]
	v_mfma_f32_16x16x32_bf16 v[92:95], v[156:159], v[190:193], v[92:95]
	v_mfma_f32_16x16x32_bf16 v[88:91], v[174:177], v[190:193], v[88:91]
	v_mfma_f32_16x16x32_bf16 v[84:87], v[156:159], v[210:213], v[84:87]
	v_mfma_f32_16x16x32_bf16 v[80:83], v[174:177], v[210:213], v[80:83]
	v_mfma_f32_16x16x32_bf16 v[72:75], v[156:159], v[244:247], v[72:75]
	v_mfma_f32_16x16x32_bf16 v[64:67], v[174:177], v[244:247], v[64:67]
	s_barrier
	s_add_i32 s34, s57, s0
	s_mov_b32 m0, s34
	ds_read_b128 v[178:181], v199 offset:16384
	ds_read_b128 v[182:185], v199 offset:17408
	ds_read_b128 v[186:189], v199 offset:18432
	ds_read_b128 v[190:193], v199 offset:19456
	ds_read_b128 v[194:197], v199 offset:20480
	ds_read_b128 v[210:213], v199 offset:21504
	ds_read_b128 v[240:243], v199 offset:22528
	ds_read_b128 v[244:247], v199 offset:23552
	global_load_lds_dwordx4 v32, s[52:53]
	s_add_i32 m0, s34, 0x2000
	s_add_u32 s34, s52, 0x4000
	s_addc_u32 s35, s53, 0
	s_add_i32 s57, s69, s0
	global_load_lds_dwordx4 v166, s[52:53]
	s_mov_b32 m0, s57
	v_lshl_add_u64 v[248:249], s[54:55], 0, v[164:165]
	global_load_lds_dwordx4 v32, s[34:35]
	s_add_i32 m0, s57, 0x2000
	v_lshl_add_u64 v[250:251], s[54:55], 0, v[168:169]
	global_load_lds_dwordx4 v166, s[34:35]
	s_mov_b32 m0, s29
	s_nop 0
	global_load_lds_dwordx4 v164, s[54:55]
	s_mov_b32 m0, s45
	s_nop 0
	global_load_lds_dwordx4 v168, s[54:55]
	s_waitcnt vmcnt(8)
	s_waitcnt lgkmcnt(0)
	s_barrier
	v_mfma_f32_16x16x32_bf16 v[76:79], v[136:139], v[178:181], v[76:79]
	v_mfma_f32_16x16x32_bf16 v[68:71], v[144:147], v[178:181], v[68:71]
	v_mfma_f32_16x16x32_bf16 v[60:63], v[136:139], v[186:189], v[60:63]
	v_mfma_f32_16x16x32_bf16 v[56:59], v[144:147], v[186:189], v[56:59]
	v_mfma_f32_16x16x32_bf16 v[52:55], v[136:139], v[194:197], v[52:55]
	v_mfma_f32_16x16x32_bf16 v[48:51], v[144:147], v[194:197], v[48:51]
	v_mfma_f32_16x16x32_bf16 v[44:47], v[136:139], v[240:243], v[44:47]
	v_mfma_f32_16x16x32_bf16 v[40:43], v[144:147], v[240:243], v[40:43]
	v_mfma_f32_16x16x32_bf16 v[76:79], v[140:143], v[182:185], v[76:79]
	v_mfma_f32_16x16x32_bf16 v[68:71], v[148:151], v[182:185], v[68:71]
	v_mfma_f32_16x16x32_bf16 v[60:63], v[140:143], v[190:193], v[60:63]
	v_mfma_f32_16x16x32_bf16 v[56:59], v[148:151], v[190:193], v[56:59]
	v_mfma_f32_16x16x32_bf16 v[52:55], v[140:143], v[210:213], v[52:55]
	v_mfma_f32_16x16x32_bf16 v[48:51], v[148:151], v[210:213], v[48:51]
	v_mfma_f32_16x16x32_bf16 v[44:47], v[140:143], v[244:247], v[44:47]
	v_mfma_f32_16x16x32_bf16 v[40:43], v[148:151], v[244:247], v[40:43]
	v_mfma_f32_16x16x32_bf16 v[36:39], v[152:155], v[178:181], v[36:39]
	v_mfma_f32_16x16x32_bf16 v[28:31], v[160:163], v[178:181], v[28:31]
	v_mfma_f32_16x16x32_bf16 v[24:27], v[152:155], v[186:189], v[24:27]
	v_mfma_f32_16x16x32_bf16 v[20:23], v[160:163], v[186:189], v[20:23]
	v_mfma_f32_16x16x32_bf16 v[16:19], v[152:155], v[194:197], v[16:19]
	v_mfma_f32_16x16x32_bf16 v[12:15], v[160:163], v[194:197], v[12:15]
	v_mfma_f32_16x16x32_bf16 v[8:11], v[152:155], v[240:243], v[8:11]
	v_mfma_f32_16x16x32_bf16 v[2:5], v[160:163], v[240:243], v[4:7]
	v_mfma_f32_16x16x32_bf16 v[36:39], v[156:159], v[182:185], v[36:39]
	v_mfma_f32_16x16x32_bf16 v[28:31], v[174:177], v[182:185], v[28:31]
	v_mfma_f32_16x16x32_bf16 v[24:27], v[156:159], v[190:193], v[24:27]
	v_mfma_f32_16x16x32_bf16 v[20:23], v[174:177], v[190:193], v[20:23]
	v_mfma_f32_16x16x32_bf16 v[16:19], v[156:159], v[210:213], v[16:19]
	v_mfma_f32_16x16x32_bf16 v[12:15], v[174:177], v[210:213], v[12:15]
	v_mfma_f32_16x16x32_bf16 v[8:11], v[156:159], v[244:247], v[8:11]
	v_mfma_f32_16x16x32_bf16 v[2:5], v[174:177], v[244:247], v[2:5]
	s_barrier
	s_add_i32 s57, 0, 0x18000
	v_add_u32_e32 v0, s57, v198
	s_add_i32 s69, 0, 0x1c000
	ds_read_b128 v[136:139], v0
	ds_read_b128 v[140:143], v0 offset:1024
	ds_read_b128 v[144:147], v0 offset:2048
	ds_read_b128 v[148:151], v0 offset:3072
	v_add_u32_e32 v0, s69, v198
	ds_read_b128 v[152:155], v0
	ds_read_b128 v[156:159], v0 offset:1024
	ds_read_b128 v[160:163], v0 offset:2048
	ds_read_b128 v[174:177], v0 offset:3072
	s_add_u32 s34, s54, 0x80000
	s_addc_u32 s35, s55, 0
	s_mov_b32 m0, s82
	ds_read_b128 v[178:181], v199 offset:32768
	ds_read_b128 v[182:185], v199 offset:33792
	ds_read_b128 v[186:189], v199 offset:34816
	ds_read_b128 v[190:193], v199 offset:35840
	ds_read_b128 v[194:197], v199 offset:36864
	ds_read_b128 v[210:213], v199 offset:37888
	ds_read_b128 v[240:243], v199 offset:38912
	ds_read_b128 v[244:247], v199 offset:39936
	global_load_lds_dwordx4 v164, s[34:35]
	s_mov_b32 m0, s90
	s_nop 0
	global_load_lds_dwordx4 v168, s[34:35]
	s_waitcnt vmcnt(8)
	s_waitcnt lgkmcnt(0)
	s_barrier
	v_mfma_f32_16x16x32_bf16 v[132:135], v[136:139], v[178:181], v[132:135]
	v_mfma_f32_16x16x32_bf16 v[128:131], v[144:147], v[178:181], v[128:131]
	v_mfma_f32_16x16x32_bf16 v[124:127], v[136:139], v[186:189], v[124:127]
	v_mfma_f32_16x16x32_bf16 v[120:123], v[144:147], v[186:189], v[120:123]
	v_mfma_f32_16x16x32_bf16 v[116:119], v[136:139], v[194:197], v[116:119]
	v_mfma_f32_16x16x32_bf16 v[112:115], v[144:147], v[194:197], v[112:115]
	v_mfma_f32_16x16x32_bf16 v[108:111], v[136:139], v[240:243], v[108:111]
	v_mfma_f32_16x16x32_bf16 v[104:107], v[144:147], v[240:243], v[104:107]
	v_mfma_f32_16x16x32_bf16 v[132:135], v[140:143], v[182:185], v[132:135]
	v_mfma_f32_16x16x32_bf16 v[128:131], v[148:151], v[182:185], v[128:131]
	v_mfma_f32_16x16x32_bf16 v[124:127], v[140:143], v[190:193], v[124:127]
	v_mfma_f32_16x16x32_bf16 v[120:123], v[148:151], v[190:193], v[120:123]
	v_mfma_f32_16x16x32_bf16 v[116:119], v[140:143], v[210:213], v[116:119]
	v_mfma_f32_16x16x32_bf16 v[112:115], v[148:151], v[210:213], v[112:115]
	v_mfma_f32_16x16x32_bf16 v[108:111], v[140:143], v[244:247], v[108:111]
	v_mfma_f32_16x16x32_bf16 v[104:107], v[148:151], v[244:247], v[104:107]
	v_mfma_f32_16x16x32_bf16 v[100:103], v[152:155], v[178:181], v[100:103]
	v_mfma_f32_16x16x32_bf16 v[96:99], v[160:163], v[178:181], v[96:99]
	v_mfma_f32_16x16x32_bf16 v[92:95], v[152:155], v[186:189], v[92:95]
	v_mfma_f32_16x16x32_bf16 v[88:91], v[160:163], v[186:189], v[88:91]
	v_mfma_f32_16x16x32_bf16 v[84:87], v[152:155], v[194:197], v[84:87]
	v_mfma_f32_16x16x32_bf16 v[80:83], v[160:163], v[194:197], v[80:83]
	v_mfma_f32_16x16x32_bf16 v[72:75], v[152:155], v[240:243], v[72:75]
	v_mfma_f32_16x16x32_bf16 v[64:67], v[160:163], v[240:243], v[64:67]
	v_mfma_f32_16x16x32_bf16 v[100:103], v[156:159], v[182:185], v[100:103]
	v_mfma_f32_16x16x32_bf16 v[96:99], v[174:177], v[182:185], v[96:99]
	v_mfma_f32_16x16x32_bf16 v[92:95], v[156:159], v[190:193], v[92:95]
	v_mfma_f32_16x16x32_bf16 v[88:91], v[174:177], v[190:193], v[88:91]
	v_mfma_f32_16x16x32_bf16 v[84:87], v[156:159], v[210:213], v[84:87]
	v_mfma_f32_16x16x32_bf16 v[80:83], v[174:177], v[210:213], v[80:83]
	v_mfma_f32_16x16x32_bf16 v[72:75], v[156:159], v[244:247], v[72:75]
	v_mfma_f32_16x16x32_bf16 v[64:67], v[174:177], v[244:247], v[64:67]
	s_barrier
	s_add_u32 s34, s52, 0x8000
	s_addc_u32 s35, s53, 0
	s_add_i32 s54, s57, s0
	s_mov_b32 m0, s54
	ds_read_b128 v[178:181], v199 offset:49152
	ds_read_b128 v[182:185], v199 offset:50176
	ds_read_b128 v[186:189], v199 offset:51200
	ds_read_b128 v[190:193], v199 offset:52224
	ds_read_b128 v[194:197], v199 offset:53248
	ds_read_b128 v[210:213], v199 offset:54272
	ds_read_b128 v[240:243], v199 offset:55296
	ds_read_b128 v[244:247], v199 offset:56320
	global_load_lds_dwordx4 v32, s[34:35]
	s_add_i32 m0, s54, 0x2000
	v_lshl_add_u64 v[6:7], s[34:35], 0, v[166:167]
	s_add_u32 s34, s52, 0xc000
	s_addc_u32 s35, s53, 0
	s_add_i32 s52, s69, s0
	global_load_lds_dwordx4 v[6:7], off
	s_mov_b32 m0, s52
	s_nop 0
	global_load_lds_dwordx4 v32, s[34:35]
	s_add_i32 m0, s52, 0x2000
	s_nop 0
	global_load_lds_dwordx4 v166, s[34:35]
	v_lshl_add_u64 v[6:7], v[248:249], 0, s[92:93]
	s_mov_b32 m0, s91
	s_nop 0
	global_load_lds_dwordx4 v[6:7], off
	v_lshl_add_u64 v[6:7], v[250:251], 0, s[92:93]
	s_mov_b32 m0, s30
	s_nop 0
	global_load_lds_dwordx4 v[6:7], off
	s_waitcnt vmcnt(8)
	s_waitcnt lgkmcnt(0)
	s_barrier
	v_mfma_f32_16x16x32_bf16 v[76:79], v[136:139], v[178:181], v[76:79]
	v_mfma_f32_16x16x32_bf16 v[68:71], v[144:147], v[178:181], v[68:71]
	v_mfma_f32_16x16x32_bf16 v[60:63], v[136:139], v[186:189], v[60:63]
	v_mfma_f32_16x16x32_bf16 v[56:59], v[144:147], v[186:189], v[56:59]
	v_mfma_f32_16x16x32_bf16 v[52:55], v[136:139], v[194:197], v[52:55]
	v_mfma_f32_16x16x32_bf16 v[48:51], v[144:147], v[194:197], v[48:51]
	v_mfma_f32_16x16x32_bf16 v[44:47], v[136:139], v[240:243], v[44:47]
	v_mfma_f32_16x16x32_bf16 v[40:43], v[144:147], v[240:243], v[40:43]
	v_mfma_f32_16x16x32_bf16 v[76:79], v[140:143], v[182:185], v[76:79]
	v_mfma_f32_16x16x32_bf16 v[68:71], v[148:151], v[182:185], v[68:71]
	v_mfma_f32_16x16x32_bf16 v[60:63], v[140:143], v[190:193], v[60:63]
	v_mfma_f32_16x16x32_bf16 v[56:59], v[148:151], v[190:193], v[56:59]
	v_mfma_f32_16x16x32_bf16 v[52:55], v[140:143], v[210:213], v[52:55]
	v_mfma_f32_16x16x32_bf16 v[48:51], v[148:151], v[210:213], v[48:51]
	v_mfma_f32_16x16x32_bf16 v[44:47], v[140:143], v[244:247], v[44:47]
	v_mfma_f32_16x16x32_bf16 v[40:43], v[148:151], v[244:247], v[40:43]
	v_mfma_f32_16x16x32_bf16 v[36:39], v[152:155], v[178:181], v[36:39]
	v_mfma_f32_16x16x32_bf16 v[28:31], v[160:163], v[178:181], v[28:31]
	v_mfma_f32_16x16x32_bf16 v[24:27], v[152:155], v[186:189], v[24:27]
	v_mfma_f32_16x16x32_bf16 v[20:23], v[160:163], v[186:189], v[20:23]
	v_mfma_f32_16x16x32_bf16 v[16:19], v[152:155], v[194:197], v[16:19]
	v_mfma_f32_16x16x32_bf16 v[12:15], v[160:163], v[194:197], v[12:15]
	v_mfma_f32_16x16x32_bf16 v[6:9], v[152:155], v[240:243], v[8:11]
	v_mfma_f32_16x16x32_bf16 v[2:5], v[160:163], v[240:243], v[2:5]
	v_mfma_f32_16x16x32_bf16 v[36:39], v[156:159], v[182:185], v[36:39]
	v_mfma_f32_16x16x32_bf16 v[28:31], v[174:177], v[182:185], v[28:31]
	v_mfma_f32_16x16x32_bf16 v[24:27], v[156:159], v[190:193], v[24:27]
	v_mfma_f32_16x16x32_bf16 v[20:23], v[174:177], v[190:193], v[20:23]
	v_mfma_f32_16x16x32_bf16 v[16:19], v[156:159], v[210:213], v[16:19]
	v_mfma_f32_16x16x32_bf16 v[12:15], v[174:177], v[210:213], v[12:15]
	v_mfma_f32_16x16x32_bf16 v[8:11], v[156:159], v[244:247], v[6:9]
	v_mfma_f32_16x16x32_bf16 v[4:7], v[174:177], v[244:247], v[2:5]
	s_barrier
	s_add_i32 s56, s56, 2
	s_add_u32 s15, s15, 0x10000
	s_addc_u32 s51, s51, 0
	s_add_u32 s48, s48, 0x100
	s_addc_u32 s49, s49, 0
	s_cmp_gt_u32 s56, 29
	s_cbranch_scc0 .LBB0_788
	s_and_b64 vcc, exec, s[46:47]
	s_cbranch_vccz .LBB0_791
	s_barrier

.LBB0_877:
	s_add_u32 s62, s60, 0x100
	s_addc_u32 s63, s61, 0
	s_add_i32 s34, 0, 0x10000
	s_cmp_eq_u32 s49, 60
	s_cselect_b32 s67, s51, s63
	s_cselect_b32 s66, s50, s62
	v_add_u32_e32 v0, s34, v188
	s_cselect_b32 s65, s53, s28
	s_cselect_b32 s64, s52, s13
	s_add_i32 s55, 0, 0x14000
	ds_read_b128 v[132:135], v0
	ds_read_b128 v[136:139], v0 offset:1024
	ds_read_b128 v[140:143], v0 offset:2048
	ds_read_b128 v[144:147], v0 offset:3072
	v_add_u32_e32 v0, s55, v188
	ds_read_b128 v[148:151], v0
	ds_read_b128 v[152:155], v0 offset:1024
	ds_read_b128 v[168:171], v0 offset:2048
	ds_read_b128 v[172:175], v0 offset:3072
	s_add_i32 m0, s29, 0xc000
	ds_read_b128 v[176:179], v189
	ds_read_b128 v[180:183], v189 offset:1024
	ds_read_b128 v[184:187], v189 offset:2048
	ds_read_b128 v[192:195], v189 offset:3072
	ds_read_b128 v[210:213], v189 offset:4096
	ds_read_b128 v[234:237], v189 offset:5120
	ds_read_b128 v[238:241], v189 offset:6144
	ds_read_b128 v[242:245], v189 offset:7168
	global_load_lds_dwordx4 v164, s[60:61]
	s_add_i32 m0, s29, 0xe000
	s_nop 0
	global_load_lds_dwordx4 v166, s[60:61]
	s_waitcnt vmcnt(8)
	s_waitcnt lgkmcnt(0)
	s_barrier
	v_mfma_f32_16x16x32_bf16 v[128:131], v[132:135], v[176:179], v[128:131]
	v_mfma_f32_16x16x32_bf16 v[124:127], v[140:143], v[176:179], v[124:127]
	v_mfma_f32_16x16x32_bf16 v[112:115], v[132:135], v[184:187], v[112:115]
	v_mfma_f32_16x16x32_bf16 v[108:111], v[140:143], v[184:187], v[108:111]
	v_mfma_f32_16x16x32_bf16 v[96:99], v[132:135], v[210:213], v[96:99]
	v_mfma_f32_16x16x32_bf16 v[92:95], v[140:143], v[210:213], v[92:95]
	v_mfma_f32_16x16x32_bf16 v[80:83], v[132:135], v[238:241], v[80:83]
	v_mfma_f32_16x16x32_bf16 v[76:79], v[140:143], v[238:241], v[76:79]
	v_mfma_f32_16x16x32_bf16 v[128:131], v[136:139], v[180:183], v[128:131]
	v_mfma_f32_16x16x32_bf16 v[124:127], v[144:147], v[180:183], v[124:127]
	v_mfma_f32_16x16x32_bf16 v[112:115], v[136:139], v[192:195], v[112:115]
	v_mfma_f32_16x16x32_bf16 v[108:111], v[144:147], v[192:195], v[108:111]
	v_mfma_f32_16x16x32_bf16 v[96:99], v[136:139], v[234:237], v[96:99]
	v_mfma_f32_16x16x32_bf16 v[92:95], v[144:147], v[234:237], v[92:95]
	v_mfma_f32_16x16x32_bf16 v[80:83], v[136:139], v[242:245], v[80:83]
	v_mfma_f32_16x16x32_bf16 v[76:79], v[144:147], v[242:245], v[76:79]
	v_mfma_f32_16x16x32_bf16 v[120:123], v[148:151], v[176:179], v[120:123]
	v_mfma_f32_16x16x32_bf16 v[116:119], v[168:171], v[176:179], v[116:119]
	v_mfma_f32_16x16x32_bf16 v[104:107], v[148:151], v[184:187], v[104:107]
	v_mfma_f32_16x16x32_bf16 v[100:103], v[168:171], v[184:187], v[100:103]
	v_mfma_f32_16x16x32_bf16 v[88:91], v[148:151], v[210:213], v[88:91]
	v_mfma_f32_16x16x32_bf16 v[84:87], v[168:171], v[210:213], v[84:87]
	v_mfma_f32_16x16x32_bf16 v[72:75], v[148:151], v[238:241], v[72:75]
	v_mfma_f32_16x16x32_bf16 v[68:71], v[168:171], v[238:241], v[68:71]
	v_mfma_f32_16x16x32_bf16 v[120:123], v[152:155], v[180:183], v[120:123]
	v_mfma_f32_16x16x32_bf16 v[116:119], v[172:175], v[180:183], v[116:119]
	v_mfma_f32_16x16x32_bf16 v[104:107], v[152:155], v[192:195], v[104:107]
	v_mfma_f32_16x16x32_bf16 v[100:103], v[172:175], v[192:195], v[100:103]
	v_mfma_f32_16x16x32_bf16 v[88:91], v[152:155], v[234:237], v[88:91]
	v_mfma_f32_16x16x32_bf16 v[84:87], v[172:175], v[234:237], v[84:87]
	v_mfma_f32_16x16x32_bf16 v[72:75], v[152:155], v[242:245], v[72:75]
	v_mfma_f32_16x16x32_bf16 v[68:71], v[172:175], v[242:245], v[68:71]
	s_barrier
	s_add_i32 s34, s34, s0
	s_mov_b32 m0, s34
	ds_read_b128 v[176:179], v189 offset:16384
	ds_read_b128 v[180:183], v189 offset:17408
	ds_read_b128 v[184:187], v189 offset:18432
	ds_read_b128 v[192:195], v189 offset:19456
	ds_read_b128 v[210:213], v189 offset:20480
	ds_read_b128 v[234:237], v189 offset:21504
	ds_read_b128 v[238:241], v189 offset:22528
	ds_read_b128 v[242:245], v189 offset:23552
	global_load_lds_dwordx4 v156, s[64:65]
	s_add_i32 m0, s34, 0x2000
	s_add_u32 s34, s64, 0x4000
	s_addc_u32 s35, s65, 0
	s_add_i32 s55, s55, s0
	global_load_lds_dwordx4 v160, s[64:65]
	s_mov_b32 m0, s55
	s_nop 0
	global_load_lds_dwordx4 v156, s[34:35]
	s_add_i32 m0, s55, 0x2000
	s_nop 0
	global_load_lds_dwordx4 v160, s[34:35]
	s_mov_b32 m0, s29
	s_nop 0
	global_load_lds_dwordx4 v158, s[66:67]
	s_mov_b32 m0, s45
	s_nop 0
	global_load_lds_dwordx4 v162, s[66:67]
	s_waitcnt vmcnt(8)
	s_waitcnt lgkmcnt(0)
	s_barrier
	v_mfma_f32_16x16x32_bf16 v[64:67], v[132:135], v[176:179], v[64:67]
	v_mfma_f32_16x16x32_bf16 v[60:63], v[140:143], v[176:179], v[60:63]
	v_mfma_f32_16x16x32_bf16 v[48:51], v[132:135], v[184:187], v[48:51]
	v_mfma_f32_16x16x32_bf16 v[44:47], v[140:143], v[184:187], v[44:47]
	v_mfma_f32_16x16x32_bf16 v[30:33], v[132:135], v[210:213], v[30:33]
	v_mfma_f32_16x16x32_bf16 v[26:29], v[140:143], v[210:213], v[26:29]
	v_mfma_f32_16x16x32_bf16 v[14:17], v[132:135], v[238:241], v[14:17]
	v_mfma_f32_16x16x32_bf16 v[10:13], v[140:143], v[238:241], v[10:13]
	v_mfma_f32_16x16x32_bf16 v[64:67], v[136:139], v[180:183], v[64:67]
	v_mfma_f32_16x16x32_bf16 v[60:63], v[144:147], v[180:183], v[60:63]
	v_mfma_f32_16x16x32_bf16 v[48:51], v[136:139], v[192:195], v[48:51]
	v_mfma_f32_16x16x32_bf16 v[44:47], v[144:147], v[192:195], v[44:47]
	v_mfma_f32_16x16x32_bf16 v[30:33], v[136:139], v[234:237], v[30:33]
	v_mfma_f32_16x16x32_bf16 v[26:29], v[144:147], v[234:237], v[26:29]
	v_mfma_f32_16x16x32_bf16 v[14:17], v[136:139], v[242:245], v[14:17]
	v_mfma_f32_16x16x32_bf16 v[10:13], v[144:147], v[242:245], v[10:13]
	v_mfma_f32_16x16x32_bf16 v[56:59], v[148:151], v[176:179], v[56:59]
	v_mfma_f32_16x16x32_bf16 v[52:55], v[168:171], v[176:179], v[52:55]
	v_mfma_f32_16x16x32_bf16 v[40:43], v[148:151], v[184:187], v[40:43]
	v_mfma_f32_16x16x32_bf16 v[36:39], v[168:171], v[184:187], v[36:39]
	v_mfma_f32_16x16x32_bf16 v[22:25], v[148:151], v[210:213], v[22:25]
	v_mfma_f32_16x16x32_bf16 v[18:21], v[168:171], v[210:213], v[18:21]
	v_mfma_f32_16x16x32_bf16 v[6:9], v[148:151], v[238:241], v[6:9]
	v_mfma_f32_16x16x32_bf16 v[2:5], v[168:171], v[238:241], v[2:5]
	v_mfma_f32_16x16x32_bf16 v[56:59], v[152:155], v[180:183], v[56:59]
	v_mfma_f32_16x16x32_bf16 v[52:55], v[172:175], v[180:183], v[52:55]
	v_mfma_f32_16x16x32_bf16 v[40:43], v[152:155], v[192:195], v[40:43]
	v_mfma_f32_16x16x32_bf16 v[36:39], v[172:175], v[192:195], v[36:39]
	v_mfma_f32_16x16x32_bf16 v[22:25], v[152:155], v[234:237], v[22:25]
	v_mfma_f32_16x16x32_bf16 v[18:21], v[172:175], v[234:237], v[18:21]
	v_mfma_f32_16x16x32_bf16 v[6:9], v[152:155], v[242:245], v[6:9]
	v_mfma_f32_16x16x32_bf16 v[2:5], v[172:175], v[242:245], v[2:5]
	s_barrier
	s_add_i32 s55, 0, 0x18000
	v_add_u32_e32 v0, s55, v188
	s_add_i32 s58, 0, 0x1c000
	ds_read_b128 v[132:135], v0
	ds_read_b128 v[136:139], v0 offset:1024
	ds_read_b128 v[140:143], v0 offset:2048
	ds_read_b128 v[144:147], v0 offset:3072
	v_add_u32_e32 v0, s58, v188
	ds_read_b128 v[148:151], v0
	ds_read_b128 v[152:155], v0 offset:1024
	ds_read_b128 v[168:171], v0 offset:2048
	ds_read_b128 v[172:175], v0 offset:3072
	s_add_u32 s34, s66, 0x100000
	s_addc_u32 s35, s67, 0
	s_mov_b32 m0, s82
	ds_read_b128 v[176:179], v189 offset:32768
	ds_read_b128 v[180:183], v189 offset:33792
	ds_read_b128 v[184:187], v189 offset:34816
	ds_read_b128 v[192:195], v189 offset:35840
	ds_read_b128 v[210:213], v189 offset:36864
	ds_read_b128 v[234:237], v189 offset:37888
	ds_read_b128 v[238:241], v189 offset:38912
	ds_read_b128 v[242:245], v189 offset:39936
	global_load_lds_dwordx4 v158, s[34:35]
	s_mov_b32 m0, s90
	s_nop 0
	global_load_lds_dwordx4 v162, s[34:35]
	s_waitcnt vmcnt(8)
	s_waitcnt lgkmcnt(0)
	s_barrier
	v_mfma_f32_16x16x32_bf16 v[128:131], v[132:135], v[176:179], v[128:131]
	v_mfma_f32_16x16x32_bf16 v[124:127], v[140:143], v[176:179], v[124:127]
	v_mfma_f32_16x16x32_bf16 v[112:115], v[132:135], v[184:187], v[112:115]
	v_mfma_f32_16x16x32_bf16 v[108:111], v[140:143], v[184:187], v[108:111]
	v_mfma_f32_16x16x32_bf16 v[96:99], v[132:135], v[210:213], v[96:99]
	v_mfma_f32_16x16x32_bf16 v[92:95], v[140:143], v[210:213], v[92:95]
	v_mfma_f32_16x16x32_bf16 v[80:83], v[132:135], v[238:241], v[80:83]
	v_mfma_f32_16x16x32_bf16 v[76:79], v[140:143], v[238:241], v[76:79]
	v_mfma_f32_16x16x32_bf16 v[128:131], v[136:139], v[180:183], v[128:131]
	v_mfma_f32_16x16x32_bf16 v[124:127], v[144:147], v[180:183], v[124:127]
	v_mfma_f32_16x16x32_bf16 v[112:115], v[136:139], v[192:195], v[112:115]
	v_mfma_f32_16x16x32_bf16 v[108:111], v[144:147], v[192:195], v[108:111]
	v_mfma_f32_16x16x32_bf16 v[96:99], v[136:139], v[234:237], v[96:99]
	v_mfma_f32_16x16x32_bf16 v[92:95], v[144:147], v[234:237], v[92:95]
	v_mfma_f32_16x16x32_bf16 v[80:83], v[136:139], v[242:245], v[80:83]
	v_mfma_f32_16x16x32_bf16 v[76:79], v[144:147], v[242:245], v[76:79]
	v_mfma_f32_16x16x32_bf16 v[120:123], v[148:151], v[176:179], v[120:123]
	v_mfma_f32_16x16x32_bf16 v[116:119], v[168:171], v[176:179], v[116:119]
	v_mfma_f32_16x16x32_bf16 v[104:107], v[148:151], v[184:187], v[104:107]
	v_mfma_f32_16x16x32_bf16 v[100:103], v[168:171], v[184:187], v[100:103]
	v_mfma_f32_16x16x32_bf16 v[88:91], v[148:151], v[210:213], v[88:91]
	v_mfma_f32_16x16x32_bf16 v[84:87], v[168:171], v[210:213], v[84:87]
	v_mfma_f32_16x16x32_bf16 v[72:75], v[148:151], v[238:241], v[72:75]
	v_mfma_f32_16x16x32_bf16 v[68:71], v[168:171], v[238:241], v[68:71]
	v_mfma_f32_16x16x32_bf16 v[120:123], v[152:155], v[180:183], v[120:123]
	v_mfma_f32_16x16x32_bf16 v[116:119], v[172:175], v[180:183], v[116:119]
	v_mfma_f32_16x16x32_bf16 v[104:107], v[152:155], v[192:195], v[104:107]
	v_mfma_f32_16x16x32_bf16 v[100:103], v[172:175], v[192:195], v[100:103]
	v_mfma_f32_16x16x32_bf16 v[88:91], v[152:155], v[234:237], v[88:91]
	v_mfma_f32_16x16x32_bf16 v[84:87], v[172:175], v[234:237], v[84:87]
	v_mfma_f32_16x16x32_bf16 v[72:75], v[152:155], v[242:245], v[72:75]
	v_mfma_f32_16x16x32_bf16 v[68:71], v[172:175], v[242:245], v[68:71]
	s_barrier
	s_add_u32 s34, s64, 0x8000
	s_addc_u32 s35, s65, 0
	s_add_i32 s55, s55, s0
	s_mov_b32 m0, s55
	ds_read_b128 v[176:179], v189 offset:49152
	ds_read_b128 v[180:183], v189 offset:50176
	ds_read_b128 v[184:187], v189 offset:51200
	ds_read_b128 v[192:195], v189 offset:52224
	ds_read_b128 v[210:213], v189 offset:53248
	ds_read_b128 v[234:237], v189 offset:54272
	ds_read_b128 v[238:241], v189 offset:55296
	ds_read_b128 v[242:245], v189 offset:56320
	global_load_lds_dwordx4 v156, s[34:35]
	s_add_i32 m0, s55, 0x2000
	v_lshl_add_u64 v[250:251], s[34:35], 0, v[160:161]
	s_add_u32 s34, s64, 0xc000
	s_addc_u32 s35, s65, 0
	s_add_i32 s55, s58, s0
	global_load_lds_dwordx4 v[250:251], off
	s_mov_b32 m0, s55
	s_nop 0
	global_load_lds_dwordx4 v156, s[34:35]
	s_add_i32 m0, s55, 0x2000
	s_nop 0
	global_load_lds_dwordx4 v160, s[34:35]
	s_mov_b32 m0, s91
	s_nop 0
	s_add_u32 s100, s66, s92
	s_addc_u32 s101, s67, s93
	global_load_lds_dwordx4 v158, s[100:101]
	s_mov_b32 m0, s30
	s_nop 0
	s_add_u32 s100, s66, s92
	s_addc_u32 s101, s67, s93
	global_load_lds_dwordx4 v162, s[100:101]
	s_waitcnt vmcnt(8)
	s_waitcnt lgkmcnt(0)
	s_barrier
	v_mfma_f32_16x16x32_bf16 v[64:67], v[132:135], v[176:179], v[64:67]
	v_mfma_f32_16x16x32_bf16 v[60:63], v[140:143], v[176:179], v[60:63]
	v_mfma_f32_16x16x32_bf16 v[48:51], v[132:135], v[184:187], v[48:51]
	v_mfma_f32_16x16x32_bf16 v[44:47], v[140:143], v[184:187], v[44:47]
	v_mfma_f32_16x16x32_bf16 v[30:33], v[132:135], v[210:213], v[30:33]
	v_mfma_f32_16x16x32_bf16 v[26:29], v[140:143], v[210:213], v[26:29]
	v_mfma_f32_16x16x32_bf16 v[14:17], v[132:135], v[238:241], v[14:17]
	v_mfma_f32_16x16x32_bf16 v[10:13], v[140:143], v[238:241], v[10:13]
	v_mfma_f32_16x16x32_bf16 v[64:67], v[136:139], v[180:183], v[64:67]
	v_mfma_f32_16x16x32_bf16 v[60:63], v[144:147], v[180:183], v[60:63]
	v_mfma_f32_16x16x32_bf16 v[48:51], v[136:139], v[192:195], v[48:51]
	v_mfma_f32_16x16x32_bf16 v[44:47], v[144:147], v[192:195], v[44:47]
	v_mfma_f32_16x16x32_bf16 v[30:33], v[136:139], v[234:237], v[30:33]
	v_mfma_f32_16x16x32_bf16 v[26:29], v[144:147], v[234:237], v[26:29]
	v_mfma_f32_16x16x32_bf16 v[14:17], v[136:139], v[242:245], v[14:17]
	v_mfma_f32_16x16x32_bf16 v[10:13], v[144:147], v[242:245], v[10:13]
	v_mfma_f32_16x16x32_bf16 v[56:59], v[148:151], v[176:179], v[56:59]
	v_mfma_f32_16x16x32_bf16 v[52:55], v[168:171], v[176:179], v[52:55]
	v_mfma_f32_16x16x32_bf16 v[40:43], v[148:151], v[184:187], v[40:43]
	v_mfma_f32_16x16x32_bf16 v[36:39], v[168:171], v[184:187], v[36:39]
	v_mfma_f32_16x16x32_bf16 v[22:25], v[148:151], v[210:213], v[22:25]
	v_mfma_f32_16x16x32_bf16 v[18:21], v[168:171], v[210:213], v[18:21]
	v_mfma_f32_16x16x32_bf16 v[6:9], v[148:151], v[238:241], v[6:9]
	v_mfma_f32_16x16x32_bf16 v[2:5], v[168:171], v[238:241], v[2:5]
	v_mfma_f32_16x16x32_bf16 v[56:59], v[152:155], v[180:183], v[56:59]
	v_mfma_f32_16x16x32_bf16 v[52:55], v[172:175], v[180:183], v[52:55]
	v_mfma_f32_16x16x32_bf16 v[40:43], v[152:155], v[192:195], v[40:43]
	v_mfma_f32_16x16x32_bf16 v[36:39], v[172:175], v[192:195], v[36:39]
	v_mfma_f32_16x16x32_bf16 v[22:25], v[152:155], v[234:237], v[22:25]
	v_mfma_f32_16x16x32_bf16 v[18:21], v[172:175], v[234:237], v[18:21]
	v_mfma_f32_16x16x32_bf16 v[6:9], v[152:155], v[242:245], v[6:9]
	v_mfma_f32_16x16x32_bf16 v[2:5], v[172:175], v[242:245], v[2:5]
	s_barrier
	s_add_i32 s49, s49, 2
	s_add_u32 s13, s13, 0x10000
	s_addc_u32 s28, s28, 0
	s_cmp_gt_u32 s49, 61
	s_mov_b64 s[60:61], s[62:63]
	s_cbranch_scc0 .LBB0_877
	s_and_b64 vcc, exec, s[46:47]
	s_cbranch_vccz .LBB0_880
	s_barrier

.LBB0_1070:
	s_add_u32 s34, s12, 0xfff00080
	s_addc_u32 s35, s13, -1
	s_add_i32 s48, 0, 0x10000
	s_cmp_eq_u32 s59, 28
	s_cselect_b32 s67, s61, s35
	s_cselect_b32 s66, s60, s34
	v_add_u32_e32 v0, s48, v196
	s_cselect_b32 s65, s63, s58
	s_cselect_b32 s64, s62, s28
	s_add_i32 s49, 0, 0x14000
	ds_read_b128 v[100:103], v0
	ds_read_b128 v[112:115], v0 offset:1024
	ds_read_b128 v[172:175], v0 offset:2048
	ds_read_b128 v[188:191], v0 offset:3072
	v_add_u32_e32 v0, s49, v196
	ds_read_b128 v[192:195], v0
	ds_read_b128 v[200:203], v0 offset:1024
	ds_read_b128 v[204:207], v0 offset:2048
	ds_read_b128 v[210:213], v0 offset:3072
	s_add_i32 m0, s29, 0xc000
	ds_read_b128 v[216:219], v197
	ds_read_b128 v[220:223], v197 offset:1024
	ds_read_b128 v[224:227], v197 offset:2048
	ds_read_b128 v[228:231], v197 offset:3072
	ds_read_b128 v[232:235], v197 offset:4096
	ds_read_b128 v[236:239], v197 offset:5120
	ds_read_b128 v[240:243], v197 offset:6144
	ds_read_b128 v[244:247], v197 offset:7168
	global_load_lds_dwordx4 v184, s[12:13]
	s_add_i32 m0, s29, 0xe000
	s_nop 0
	global_load_lds_dwordx4 v186, s[12:13]
	s_waitcnt vmcnt(8)
	s_waitcnt lgkmcnt(0)
	s_barrier
	v_mfma_i32_16x16x64_i8 v[168:171], v[100:103], v[216:219], v[168:171]
	v_mfma_i32_16x16x64_i8 v[160:163], v[172:175], v[216:219], v[160:163]
	v_mfma_i32_16x16x64_i8 v[152:155], v[100:103], v[224:227], v[152:155]
	v_mfma_i32_16x16x64_i8 v[144:147], v[172:175], v[224:227], v[144:147]
	v_mfma_i32_16x16x64_i8 v[136:139], v[100:103], v[232:235], v[136:139]
	v_mfma_i32_16x16x64_i8 v[128:131], v[172:175], v[232:235], v[128:131]
	v_mfma_i32_16x16x64_i8 v[120:123], v[100:103], v[240:243], v[120:123]
	v_mfma_i32_16x16x64_i8 v[108:111], v[172:175], v[240:243], v[108:111]
	v_mfma_i32_16x16x64_i8 v[168:171], v[112:115], v[220:223], v[168:171]
	v_mfma_i32_16x16x64_i8 v[160:163], v[188:191], v[220:223], v[160:163]
	v_mfma_i32_16x16x64_i8 v[152:155], v[112:115], v[228:231], v[152:155]
	v_mfma_i32_16x16x64_i8 v[144:147], v[188:191], v[228:231], v[144:147]
	v_mfma_i32_16x16x64_i8 v[136:139], v[112:115], v[236:239], v[136:139]
	v_mfma_i32_16x16x64_i8 v[128:131], v[188:191], v[236:239], v[128:131]
	v_mfma_i32_16x16x64_i8 v[120:123], v[112:115], v[244:247], v[120:123]
	v_mfma_i32_16x16x64_i8 v[108:111], v[188:191], v[244:247], v[108:111]
	v_mfma_i32_16x16x64_i8 v[164:167], v[192:195], v[216:219], v[164:167]
	v_mfma_i32_16x16x64_i8 v[156:159], v[204:207], v[216:219], v[156:159]
	v_mfma_i32_16x16x64_i8 v[148:151], v[192:195], v[224:227], v[148:151]
	v_mfma_i32_16x16x64_i8 v[140:143], v[204:207], v[224:227], v[140:143]
	v_mfma_i32_16x16x64_i8 v[132:135], v[192:195], v[232:235], v[132:135]
	v_mfma_i32_16x16x64_i8 v[124:127], v[204:207], v[232:235], v[124:127]
	v_mfma_i32_16x16x64_i8 v[116:119], v[192:195], v[240:243], v[116:119]
	v_mfma_i32_16x16x64_i8 v[104:107], v[204:207], v[240:243], v[104:107]
	v_mfma_i32_16x16x64_i8 v[164:167], v[200:203], v[220:223], v[164:167]
	v_mfma_i32_16x16x64_i8 v[156:159], v[210:213], v[220:223], v[156:159]
	v_mfma_i32_16x16x64_i8 v[148:151], v[200:203], v[228:231], v[148:151]
	v_mfma_i32_16x16x64_i8 v[140:143], v[210:213], v[228:231], v[140:143]
	v_mfma_i32_16x16x64_i8 v[132:135], v[200:203], v[236:239], v[132:135]
	v_mfma_i32_16x16x64_i8 v[124:127], v[210:213], v[236:239], v[124:127]
	v_mfma_i32_16x16x64_i8 v[116:119], v[200:203], v[244:247], v[116:119]
	v_mfma_i32_16x16x64_i8 v[104:107], v[210:213], v[244:247], v[104:107]
	s_barrier
	s_add_i32 s34, s48, s0
	s_mov_b32 m0, s34
	ds_read_b128 v[216:219], v197 offset:16384
	ds_read_b128 v[220:223], v197 offset:17408
	ds_read_b128 v[224:227], v197 offset:18432
	ds_read_b128 v[228:231], v197 offset:19456
	ds_read_b128 v[232:235], v197 offset:20480
	ds_read_b128 v[236:239], v197 offset:21504
	ds_read_b128 v[240:243], v197 offset:22528
	ds_read_b128 v[244:247], v197 offset:23552
	global_load_lds_dwordx4 v176, s[64:65]
	s_add_i32 m0, s34, 0x2000
	s_add_u32 s34, s64, 0x4000
	s_addc_u32 s35, s65, 0
	s_add_i32 s48, s49, s0
	global_load_lds_dwordx4 v180, s[64:65]
	s_mov_b32 m0, s48
	s_nop 0
	global_load_lds_dwordx4 v176, s[34:35]
	s_add_i32 m0, s48, 0x2000
	s_nop 0
	global_load_lds_dwordx4 v180, s[34:35]
	s_mov_b32 m0, s29
	s_nop 0
	global_load_lds_dwordx4 v178, s[66:67]
	s_mov_b32 m0, s45
	s_nop 0
	global_load_lds_dwordx4 v182, s[66:67]
	s_waitcnt vmcnt(8)
	s_waitcnt lgkmcnt(0)
	s_barrier
	v_mfma_i32_16x16x64_i8 v[96:99], v[100:103], v[216:219], v[96:99]
	v_mfma_i32_16x16x64_i8 v[88:91], v[172:175], v[216:219], v[88:91]
	v_mfma_i32_16x16x64_i8 v[80:83], v[100:103], v[224:227], v[80:83]
	v_mfma_i32_16x16x64_i8 v[72:75], v[172:175], v[224:227], v[72:75]
	v_mfma_i32_16x16x64_i8 v[64:67], v[100:103], v[232:235], v[64:67]
	v_mfma_i32_16x16x64_i8 v[56:59], v[172:175], v[232:235], v[56:59]
	v_mfma_i32_16x16x64_i8 v[48:51], v[100:103], v[240:243], v[48:51]
	v_mfma_i32_16x16x64_i8 v[40:43], v[172:175], v[240:243], v[40:43]
	v_mfma_i32_16x16x64_i8 v[96:99], v[112:115], v[220:223], v[96:99]
	v_mfma_i32_16x16x64_i8 v[88:91], v[188:191], v[220:223], v[88:91]
	v_mfma_i32_16x16x64_i8 v[80:83], v[112:115], v[228:231], v[80:83]
	v_mfma_i32_16x16x64_i8 v[72:75], v[188:191], v[228:231], v[72:75]
	v_mfma_i32_16x16x64_i8 v[64:67], v[112:115], v[236:239], v[64:67]
	v_mfma_i32_16x16x64_i8 v[56:59], v[188:191], v[236:239], v[56:59]
	v_mfma_i32_16x16x64_i8 v[48:51], v[112:115], v[244:247], v[48:51]
	v_mfma_i32_16x16x64_i8 v[40:43], v[188:191], v[244:247], v[40:43]
	v_mfma_i32_16x16x64_i8 v[92:95], v[192:195], v[216:219], v[92:95]
	v_mfma_i32_16x16x64_i8 v[84:87], v[204:207], v[216:219], v[84:87]
	v_mfma_i32_16x16x64_i8 v[76:79], v[192:195], v[224:227], v[76:79]
	v_mfma_i32_16x16x64_i8 v[68:71], v[204:207], v[224:227], v[68:71]
	v_mfma_i32_16x16x64_i8 v[60:63], v[192:195], v[232:235], v[60:63]
	v_mfma_i32_16x16x64_i8 v[52:55], v[204:207], v[232:235], v[52:55]
	v_mfma_i32_16x16x64_i8 v[44:47], v[192:195], v[240:243], v[44:47]
	v_mfma_i32_16x16x64_i8 v[36:39], v[204:207], v[240:243], v[36:39]
	v_mfma_i32_16x16x64_i8 v[92:95], v[200:203], v[220:223], v[92:95]
	v_mfma_i32_16x16x64_i8 v[84:87], v[210:213], v[220:223], v[84:87]
	v_mfma_i32_16x16x64_i8 v[76:79], v[200:203], v[228:231], v[76:79]
	v_mfma_i32_16x16x64_i8 v[68:71], v[210:213], v[228:231], v[68:71]
	v_mfma_i32_16x16x64_i8 v[60:63], v[200:203], v[236:239], v[60:63]
	v_mfma_i32_16x16x64_i8 v[52:55], v[210:213], v[236:239], v[52:55]
	v_mfma_i32_16x16x64_i8 v[44:47], v[200:203], v[244:247], v[44:47]
	v_mfma_i32_16x16x64_i8 v[36:39], v[210:213], v[244:247], v[36:39]
	s_barrier
	s_add_i32 s48, 0, 0x18000
	v_add_u32_e32 v0, s48, v196
	s_add_i32 s49, 0, 0x1c000
	ds_read_b128 v[100:103], v0
	ds_read_b128 v[112:115], v0 offset:1024
	ds_read_b128 v[172:175], v0 offset:2048
	ds_read_b128 v[188:191], v0 offset:3072
	v_add_u32_e32 v0, s49, v196
	ds_read_b128 v[192:195], v0
	ds_read_b128 v[200:203], v0 offset:1024
	ds_read_b128 v[204:207], v0 offset:2048
	ds_read_b128 v[210:213], v0 offset:3072
	s_add_u32 s34, s66, 0x100000
	s_addc_u32 s35, s67, 0
	s_mov_b32 m0, s82
	ds_read_b128 v[216:219], v197 offset:32768
	ds_read_b128 v[220:223], v197 offset:33792
	ds_read_b128 v[224:227], v197 offset:34816
	ds_read_b128 v[228:231], v197 offset:35840
	ds_read_b128 v[232:235], v197 offset:36864
	ds_read_b128 v[236:239], v197 offset:37888
	ds_read_b128 v[240:243], v197 offset:38912
	ds_read_b128 v[244:247], v197 offset:39936
	global_load_lds_dwordx4 v178, s[34:35]
	s_mov_b32 m0, s90
	s_nop 0
	global_load_lds_dwordx4 v182, s[34:35]
	s_waitcnt vmcnt(8)
	s_waitcnt lgkmcnt(0)
	s_barrier
	v_mfma_i32_16x16x64_i8 v[168:171], v[100:103], v[216:219], v[168:171]
	v_mfma_i32_16x16x64_i8 v[160:163], v[172:175], v[216:219], v[160:163]
	v_mfma_i32_16x16x64_i8 v[152:155], v[100:103], v[224:227], v[152:155]
	v_mfma_i32_16x16x64_i8 v[144:147], v[172:175], v[224:227], v[144:147]
	v_mfma_i32_16x16x64_i8 v[136:139], v[100:103], v[232:235], v[136:139]
	v_mfma_i32_16x16x64_i8 v[128:131], v[172:175], v[232:235], v[128:131]
	v_mfma_i32_16x16x64_i8 v[120:123], v[100:103], v[240:243], v[120:123]
	v_mfma_i32_16x16x64_i8 v[108:111], v[172:175], v[240:243], v[108:111]
	v_mfma_i32_16x16x64_i8 v[168:171], v[112:115], v[220:223], v[168:171]
	v_mfma_i32_16x16x64_i8 v[160:163], v[188:191], v[220:223], v[160:163]
	v_mfma_i32_16x16x64_i8 v[152:155], v[112:115], v[228:231], v[152:155]
	v_mfma_i32_16x16x64_i8 v[144:147], v[188:191], v[228:231], v[144:147]
	v_mfma_i32_16x16x64_i8 v[136:139], v[112:115], v[236:239], v[136:139]
	v_mfma_i32_16x16x64_i8 v[128:131], v[188:191], v[236:239], v[128:131]
	v_mfma_i32_16x16x64_i8 v[120:123], v[112:115], v[244:247], v[120:123]
	v_mfma_i32_16x16x64_i8 v[108:111], v[188:191], v[244:247], v[108:111]
	v_mfma_i32_16x16x64_i8 v[164:167], v[192:195], v[216:219], v[164:167]
	v_mfma_i32_16x16x64_i8 v[156:159], v[204:207], v[216:219], v[156:159]
	v_mfma_i32_16x16x64_i8 v[148:151], v[192:195], v[224:227], v[148:151]
	v_mfma_i32_16x16x64_i8 v[140:143], v[204:207], v[224:227], v[140:143]
	v_mfma_i32_16x16x64_i8 v[132:135], v[192:195], v[232:235], v[132:135]
	v_mfma_i32_16x16x64_i8 v[124:127], v[204:207], v[232:235], v[124:127]
	v_mfma_i32_16x16x64_i8 v[116:119], v[192:195], v[240:243], v[116:119]
	v_mfma_i32_16x16x64_i8 v[104:107], v[204:207], v[240:243], v[104:107]
	v_mfma_i32_16x16x64_i8 v[164:167], v[200:203], v[220:223], v[164:167]
	v_mfma_i32_16x16x64_i8 v[156:159], v[210:213], v[220:223], v[156:159]
	v_mfma_i32_16x16x64_i8 v[148:151], v[200:203], v[228:231], v[148:151]
	v_mfma_i32_16x16x64_i8 v[140:143], v[210:213], v[228:231], v[140:143]
	v_mfma_i32_16x16x64_i8 v[132:135], v[200:203], v[236:239], v[132:135]
	v_mfma_i32_16x16x64_i8 v[124:127], v[210:213], v[236:239], v[124:127]
	v_mfma_i32_16x16x64_i8 v[116:119], v[200:203], v[244:247], v[116:119]
	v_mfma_i32_16x16x64_i8 v[104:107], v[210:213], v[244:247], v[104:107]
	s_barrier
	s_add_u32 s34, s64, 0x8000
	s_addc_u32 s35, s65, 0
	s_add_i32 s48, s48, s0
	s_mov_b32 m0, s48
	ds_read_b128 v[216:219], v197 offset:49152
	ds_read_b128 v[220:223], v197 offset:50176
	ds_read_b128 v[224:227], v197 offset:51200
	ds_read_b128 v[228:231], v197 offset:52224
	ds_read_b128 v[232:235], v197 offset:53248
	ds_read_b128 v[236:239], v197 offset:54272
	ds_read_b128 v[240:243], v197 offset:55296
	ds_read_b128 v[244:247], v197 offset:56320
	global_load_lds_dwordx4 v176, s[34:35]
	s_add_i32 m0, s48, 0x2000
	v_lshl_add_u64 v[252:253], s[34:35], 0, v[180:181]
	s_add_u32 s34, s64, 0xc000
	s_addc_u32 s35, s65, 0
	s_add_i32 s48, s49, s0
	global_load_lds_dwordx4 v[252:253], off
	s_mov_b32 m0, s48
	s_nop 0
	global_load_lds_dwordx4 v176, s[34:35]
	s_add_i32 m0, s48, 0x2000
	s_nop 0
	global_load_lds_dwordx4 v180, s[34:35]
	s_mov_b32 m0, s91
	s_nop 0
	s_add_u32 s100, s66, s92
	s_addc_u32 s101, s67, s93
	global_load_lds_dwordx4 v178, s[100:101]
	s_mov_b32 m0, s30
	s_nop 0
	s_add_u32 s100, s66, s92
	s_addc_u32 s101, s67, s93
	global_load_lds_dwordx4 v182, s[100:101]
	s_waitcnt vmcnt(8)
	s_waitcnt lgkmcnt(0)
	s_barrier
	v_mfma_i32_16x16x64_i8 v[96:99], v[100:103], v[216:219], v[96:99]
	v_mfma_i32_16x16x64_i8 v[88:91], v[172:175], v[216:219], v[88:91]
	v_mfma_i32_16x16x64_i8 v[80:83], v[100:103], v[224:227], v[80:83]
	v_mfma_i32_16x16x64_i8 v[72:75], v[172:175], v[224:227], v[72:75]
	v_mfma_i32_16x16x64_i8 v[64:67], v[100:103], v[232:235], v[64:67]
	v_mfma_i32_16x16x64_i8 v[56:59], v[172:175], v[232:235], v[56:59]
	v_mfma_i32_16x16x64_i8 v[48:51], v[100:103], v[240:243], v[48:51]
	v_mfma_i32_16x16x64_i8 v[40:43], v[172:175], v[240:243], v[40:43]
	v_mfma_i32_16x16x64_i8 v[96:99], v[112:115], v[220:223], v[96:99]
	v_mfma_i32_16x16x64_i8 v[88:91], v[188:191], v[220:223], v[88:91]
	v_mfma_i32_16x16x64_i8 v[80:83], v[112:115], v[228:231], v[80:83]
	v_mfma_i32_16x16x64_i8 v[72:75], v[188:191], v[228:231], v[72:75]
	v_mfma_i32_16x16x64_i8 v[64:67], v[112:115], v[236:239], v[64:67]
	v_mfma_i32_16x16x64_i8 v[56:59], v[188:191], v[236:239], v[56:59]
	v_mfma_i32_16x16x64_i8 v[48:51], v[112:115], v[244:247], v[48:51]
	v_mfma_i32_16x16x64_i8 v[40:43], v[188:191], v[244:247], v[40:43]
	v_mfma_i32_16x16x64_i8 v[92:95], v[192:195], v[216:219], v[92:95]
	v_mfma_i32_16x16x64_i8 v[84:87], v[204:207], v[216:219], v[84:87]
	v_mfma_i32_16x16x64_i8 v[76:79], v[192:195], v[224:227], v[76:79]
	v_mfma_i32_16x16x64_i8 v[68:71], v[204:207], v[224:227], v[68:71]
	v_mfma_i32_16x16x64_i8 v[60:63], v[192:195], v[232:235], v[60:63]
	v_mfma_i32_16x16x64_i8 v[52:55], v[204:207], v[232:235], v[52:55]
	v_mfma_i32_16x16x64_i8 v[44:47], v[192:195], v[240:243], v[44:47]
	v_mfma_i32_16x16x64_i8 v[36:39], v[204:207], v[240:243], v[36:39]
	v_mfma_i32_16x16x64_i8 v[92:95], v[200:203], v[220:223], v[92:95]
	v_mfma_i32_16x16x64_i8 v[84:87], v[210:213], v[220:223], v[84:87]
	v_mfma_i32_16x16x64_i8 v[76:79], v[200:203], v[228:231], v[76:79]
	v_mfma_i32_16x16x64_i8 v[68:71], v[210:213], v[228:231], v[68:71]
	v_mfma_i32_16x16x64_i8 v[60:63], v[200:203], v[236:239], v[60:63]
	v_mfma_i32_16x16x64_i8 v[52:55], v[210:213], v[236:239], v[52:55]
	v_mfma_i32_16x16x64_i8 v[44:47], v[200:203], v[244:247], v[44:47]
	v_mfma_i32_16x16x64_i8 v[36:39], v[210:213], v[244:247], v[36:39]
	s_barrier
	s_add_i32 s59, s59, 2
	s_add_u32 s28, s28, 0x10000
	s_addc_u32 s58, s58, 0
	s_add_u32 s12, s12, 0x100
	s_addc_u32 s13, s13, 0
	s_cmp_gt_u32 s59, 29
	s_cbranch_scc0 .LBB0_1070
	s_and_b64 vcc, exec, s[46:47]
	s_cbranch_vccz .LBB0_1073
	s_barrier

.LBB0_1261:
	s_add_u32 s42, s22, 0x100
	s_addc_u32 s43, s23, 0
	s_add_i32 s34, 0, 0x10000
	s_cmpk_eq_i32 s60, 0xa8
	s_cselect_b32 s51, s19, s43
	s_cselect_b32 s50, s18, s42
	v_add_u32_e32 v0, s34, v186
	s_cselect_b32 s49, s21, s59
	s_cselect_b32 s48, s20, s58
	s_add_i32 s35, 0, 0x14000
	ds_read_b128 v[132:135], v0
	ds_read_b128 v[136:139], v0 offset:1024
	ds_read_b128 v[140:143], v0 offset:2048
	ds_read_b128 v[144:147], v0 offset:3072
	v_add_u32_e32 v0, s35, v186
	ds_read_b128 v[148:151], v0
	ds_read_b128 v[152:155], v0 offset:1024
	ds_read_b128 v[168:171], v0 offset:2048
	ds_read_b128 v[172:175], v0 offset:3072
	s_add_i32 m0, s29, 0xc000
	ds_read_b128 v[176:179], v187
	ds_read_b128 v[180:183], v187 offset:1024
	ds_read_b128 v[192:195], v187 offset:2048
	ds_read_b128 v[210:213], v187 offset:3072
	ds_read_b128 v[232:235], v187 offset:4096
	ds_read_b128 v[236:239], v187 offset:5120
	ds_read_b128 v[240:243], v187 offset:6144
	ds_read_b128 v[244:247], v187 offset:7168
	global_load_lds_dwordx4 v164, s[22:23]
	s_add_i32 m0, s29, 0xe000
	s_nop 0
	global_load_lds_dwordx4 v166, s[22:23]
	s_waitcnt vmcnt(8)
	s_waitcnt lgkmcnt(0)
	s_barrier
	v_mfma_f32_16x16x32_bf16 v[128:131], v[132:135], v[176:179], v[128:131]
	v_mfma_f32_16x16x32_bf16 v[124:127], v[140:143], v[176:179], v[124:127]
	v_mfma_f32_16x16x32_bf16 v[112:115], v[132:135], v[192:195], v[112:115]
	v_mfma_f32_16x16x32_bf16 v[108:111], v[140:143], v[192:195], v[108:111]
	v_mfma_f32_16x16x32_bf16 v[96:99], v[132:135], v[232:235], v[96:99]
	v_mfma_f32_16x16x32_bf16 v[92:95], v[140:143], v[232:235], v[92:95]
	v_mfma_f32_16x16x32_bf16 v[80:83], v[132:135], v[240:243], v[80:83]
	v_mfma_f32_16x16x32_bf16 v[76:79], v[140:143], v[240:243], v[76:79]
	v_mfma_f32_16x16x32_bf16 v[128:131], v[136:139], v[180:183], v[128:131]
	v_mfma_f32_16x16x32_bf16 v[124:127], v[144:147], v[180:183], v[124:127]
	v_mfma_f32_16x16x32_bf16 v[112:115], v[136:139], v[210:213], v[112:115]
	v_mfma_f32_16x16x32_bf16 v[108:111], v[144:147], v[210:213], v[108:111]
	v_mfma_f32_16x16x32_bf16 v[96:99], v[136:139], v[236:239], v[96:99]
	v_mfma_f32_16x16x32_bf16 v[92:95], v[144:147], v[236:239], v[92:95]
	v_mfma_f32_16x16x32_bf16 v[80:83], v[136:139], v[244:247], v[80:83]
	v_mfma_f32_16x16x32_bf16 v[76:79], v[144:147], v[244:247], v[76:79]
	v_mfma_f32_16x16x32_bf16 v[120:123], v[148:151], v[176:179], v[120:123]
	v_mfma_f32_16x16x32_bf16 v[116:119], v[168:171], v[176:179], v[116:119]
	v_mfma_f32_16x16x32_bf16 v[104:107], v[148:151], v[192:195], v[104:107]
	v_mfma_f32_16x16x32_bf16 v[100:103], v[168:171], v[192:195], v[100:103]
	v_mfma_f32_16x16x32_bf16 v[88:91], v[148:151], v[232:235], v[88:91]
	v_mfma_f32_16x16x32_bf16 v[84:87], v[168:171], v[232:235], v[84:87]
	v_mfma_f32_16x16x32_bf16 v[72:75], v[148:151], v[240:243], v[72:75]
	v_mfma_f32_16x16x32_bf16 v[68:71], v[168:171], v[240:243], v[68:71]
	v_mfma_f32_16x16x32_bf16 v[120:123], v[152:155], v[180:183], v[120:123]
	v_mfma_f32_16x16x32_bf16 v[116:119], v[172:175], v[180:183], v[116:119]
	v_mfma_f32_16x16x32_bf16 v[104:107], v[152:155], v[210:213], v[104:107]
	v_mfma_f32_16x16x32_bf16 v[100:103], v[172:175], v[210:213], v[100:103]
	v_mfma_f32_16x16x32_bf16 v[88:91], v[152:155], v[236:239], v[88:91]
	v_mfma_f32_16x16x32_bf16 v[84:87], v[172:175], v[236:239], v[84:87]
	v_mfma_f32_16x16x32_bf16 v[72:75], v[152:155], v[244:247], v[72:75]
	v_mfma_f32_16x16x32_bf16 v[68:71], v[172:175], v[244:247], v[68:71]
	s_barrier
	s_add_i32 s22, s34, s0
	s_mov_b32 m0, s22
	ds_read_b128 v[176:179], v187 offset:16384
	ds_read_b128 v[180:183], v187 offset:17408
	ds_read_b128 v[192:195], v187 offset:18432
	ds_read_b128 v[210:213], v187 offset:19456
	ds_read_b128 v[232:235], v187 offset:20480
	ds_read_b128 v[236:239], v187 offset:21504
	ds_read_b128 v[240:243], v187 offset:22528
	ds_read_b128 v[244:247], v187 offset:23552
	global_load_lds_dwordx4 v156, s[48:49]
	s_add_i32 m0, s22, 0x2000
	s_add_u32 s22, s48, 0x4000
	s_addc_u32 s23, s49, 0
	s_add_i32 s34, s35, s0
	global_load_lds_dwordx4 v160, s[48:49]
	s_mov_b32 m0, s34
	s_nop 0
	global_load_lds_dwordx4 v156, s[22:23]
	s_add_i32 m0, s34, 0x2000
	s_nop 0
	global_load_lds_dwordx4 v160, s[22:23]
	s_mov_b32 m0, s29
	s_nop 0
	global_load_lds_dwordx4 v158, s[50:51]
	s_mov_b32 m0, s45
	s_nop 0
	global_load_lds_dwordx4 v162, s[50:51]
	s_waitcnt vmcnt(8)
	s_waitcnt lgkmcnt(0)
	s_barrier
	v_mfma_f32_16x16x32_bf16 v[64:67], v[132:135], v[176:179], v[64:67]
	v_mfma_f32_16x16x32_bf16 v[60:63], v[140:143], v[176:179], v[60:63]
	v_mfma_f32_16x16x32_bf16 v[48:51], v[132:135], v[192:195], v[48:51]
	v_mfma_f32_16x16x32_bf16 v[44:47], v[140:143], v[192:195], v[44:47]
	v_mfma_f32_16x16x32_bf16 v[30:33], v[132:135], v[232:235], v[30:33]
	v_mfma_f32_16x16x32_bf16 v[26:29], v[140:143], v[232:235], v[26:29]
	v_mfma_f32_16x16x32_bf16 v[14:17], v[132:135], v[240:243], v[14:17]
	v_mfma_f32_16x16x32_bf16 v[10:13], v[140:143], v[240:243], v[10:13]
	v_mfma_f32_16x16x32_bf16 v[64:67], v[136:139], v[180:183], v[64:67]
	v_mfma_f32_16x16x32_bf16 v[60:63], v[144:147], v[180:183], v[60:63]
	v_mfma_f32_16x16x32_bf16 v[48:51], v[136:139], v[210:213], v[48:51]
	v_mfma_f32_16x16x32_bf16 v[44:47], v[144:147], v[210:213], v[44:47]
	v_mfma_f32_16x16x32_bf16 v[30:33], v[136:139], v[236:239], v[30:33]
	v_mfma_f32_16x16x32_bf16 v[26:29], v[144:147], v[236:239], v[26:29]
	v_mfma_f32_16x16x32_bf16 v[14:17], v[136:139], v[244:247], v[14:17]
	v_mfma_f32_16x16x32_bf16 v[10:13], v[144:147], v[244:247], v[10:13]
	v_mfma_f32_16x16x32_bf16 v[56:59], v[148:151], v[176:179], v[56:59]
	v_mfma_f32_16x16x32_bf16 v[52:55], v[168:171], v[176:179], v[52:55]
	v_mfma_f32_16x16x32_bf16 v[40:43], v[148:151], v[192:195], v[40:43]
	v_mfma_f32_16x16x32_bf16 v[36:39], v[168:171], v[192:195], v[36:39]
	v_mfma_f32_16x16x32_bf16 v[22:25], v[148:151], v[232:235], v[22:25]
	v_mfma_f32_16x16x32_bf16 v[18:21], v[168:171], v[232:235], v[18:21]
	v_mfma_f32_16x16x32_bf16 v[6:9], v[148:151], v[240:243], v[6:9]
	v_mfma_f32_16x16x32_bf16 v[2:5], v[168:171], v[240:243], v[2:5]
	v_mfma_f32_16x16x32_bf16 v[56:59], v[152:155], v[180:183], v[56:59]
	v_mfma_f32_16x16x32_bf16 v[52:55], v[172:175], v[180:183], v[52:55]
	v_mfma_f32_16x16x32_bf16 v[40:43], v[152:155], v[210:213], v[40:43]
	v_mfma_f32_16x16x32_bf16 v[36:39], v[172:175], v[210:213], v[36:39]
	v_mfma_f32_16x16x32_bf16 v[22:25], v[152:155], v[236:239], v[22:25]
	v_mfma_f32_16x16x32_bf16 v[18:21], v[172:175], v[236:239], v[18:21]
	v_mfma_f32_16x16x32_bf16 v[6:9], v[152:155], v[244:247], v[6:9]
	v_mfma_f32_16x16x32_bf16 v[2:5], v[172:175], v[244:247], v[2:5]
	s_barrier
	s_add_i32 s34, 0, 0x18000
	v_add_u32_e32 v0, s34, v186
	s_add_i32 s35, 0, 0x1c000
	ds_read_b128 v[132:135], v0
	ds_read_b128 v[136:139], v0 offset:1024
	ds_read_b128 v[140:143], v0 offset:2048
	ds_read_b128 v[144:147], v0 offset:3072
	v_add_u32_e32 v0, s35, v186
	ds_read_b128 v[148:151], v0
	ds_read_b128 v[152:155], v0 offset:1024
	ds_read_b128 v[168:171], v0 offset:2048
	ds_read_b128 v[172:175], v0 offset:3072
	s_add_u32 s22, s50, 0x2b0000
	s_addc_u32 s23, s51, 0
	s_mov_b32 m0, s82
	ds_read_b128 v[176:179], v187 offset:32768
	ds_read_b128 v[180:183], v187 offset:33792
	ds_read_b128 v[192:195], v187 offset:34816
	ds_read_b128 v[210:213], v187 offset:35840
	ds_read_b128 v[232:235], v187 offset:36864
	ds_read_b128 v[236:239], v187 offset:37888
	ds_read_b128 v[240:243], v187 offset:38912
	ds_read_b128 v[244:247], v187 offset:39936
	global_load_lds_dwordx4 v158, s[22:23]
	s_mov_b32 m0, s90
	s_nop 0
	global_load_lds_dwordx4 v162, s[22:23]
	s_waitcnt vmcnt(8)
	s_waitcnt lgkmcnt(0)
	s_barrier
	v_mfma_f32_16x16x32_bf16 v[128:131], v[132:135], v[176:179], v[128:131]
	v_mfma_f32_16x16x32_bf16 v[124:127], v[140:143], v[176:179], v[124:127]
	v_mfma_f32_16x16x32_bf16 v[112:115], v[132:135], v[192:195], v[112:115]
	v_mfma_f32_16x16x32_bf16 v[108:111], v[140:143], v[192:195], v[108:111]
	v_mfma_f32_16x16x32_bf16 v[96:99], v[132:135], v[232:235], v[96:99]
	v_mfma_f32_16x16x32_bf16 v[92:95], v[140:143], v[232:235], v[92:95]
	v_mfma_f32_16x16x32_bf16 v[80:83], v[132:135], v[240:243], v[80:83]
	v_mfma_f32_16x16x32_bf16 v[76:79], v[140:143], v[240:243], v[76:79]
	v_mfma_f32_16x16x32_bf16 v[128:131], v[136:139], v[180:183], v[128:131]
	v_mfma_f32_16x16x32_bf16 v[124:127], v[144:147], v[180:183], v[124:127]
	v_mfma_f32_16x16x32_bf16 v[112:115], v[136:139], v[210:213], v[112:115]
	v_mfma_f32_16x16x32_bf16 v[108:111], v[144:147], v[210:213], v[108:111]
	v_mfma_f32_16x16x32_bf16 v[96:99], v[136:139], v[236:239], v[96:99]
	v_mfma_f32_16x16x32_bf16 v[92:95], v[144:147], v[236:239], v[92:95]
	v_mfma_f32_16x16x32_bf16 v[80:83], v[136:139], v[244:247], v[80:83]
	v_mfma_f32_16x16x32_bf16 v[76:79], v[144:147], v[244:247], v[76:79]
	v_mfma_f32_16x16x32_bf16 v[120:123], v[148:151], v[176:179], v[120:123]
	v_mfma_f32_16x16x32_bf16 v[116:119], v[168:171], v[176:179], v[116:119]
	v_mfma_f32_16x16x32_bf16 v[104:107], v[148:151], v[192:195], v[104:107]
	v_mfma_f32_16x16x32_bf16 v[100:103], v[168:171], v[192:195], v[100:103]
	v_mfma_f32_16x16x32_bf16 v[88:91], v[148:151], v[232:235], v[88:91]
	v_mfma_f32_16x16x32_bf16 v[84:87], v[168:171], v[232:235], v[84:87]
	v_mfma_f32_16x16x32_bf16 v[72:75], v[148:151], v[240:243], v[72:75]
	v_mfma_f32_16x16x32_bf16 v[68:71], v[168:171], v[240:243], v[68:71]
	v_mfma_f32_16x16x32_bf16 v[120:123], v[152:155], v[180:183], v[120:123]
	v_mfma_f32_16x16x32_bf16 v[116:119], v[172:175], v[180:183], v[116:119]
	v_mfma_f32_16x16x32_bf16 v[104:107], v[152:155], v[210:213], v[104:107]
	v_mfma_f32_16x16x32_bf16 v[100:103], v[172:175], v[210:213], v[100:103]
	v_mfma_f32_16x16x32_bf16 v[88:91], v[152:155], v[236:239], v[88:91]
	v_mfma_f32_16x16x32_bf16 v[84:87], v[172:175], v[236:239], v[84:87]
	v_mfma_f32_16x16x32_bf16 v[72:75], v[152:155], v[244:247], v[72:75]
	v_mfma_f32_16x16x32_bf16 v[68:71], v[172:175], v[244:247], v[68:71]
	s_barrier
	s_add_u32 s22, s48, 0x8000
	s_addc_u32 s23, s49, 0
	s_add_i32 s34, s34, s0
	s_mov_b32 m0, s34
	ds_read_b128 v[176:179], v187 offset:49152
	ds_read_b128 v[180:183], v187 offset:50176
	ds_read_b128 v[192:195], v187 offset:51200
	ds_read_b128 v[210:213], v187 offset:52224
	ds_read_b128 v[232:235], v187 offset:53248
	ds_read_b128 v[236:239], v187 offset:54272
	ds_read_b128 v[240:243], v187 offset:55296
	ds_read_b128 v[244:247], v187 offset:56320
	global_load_lds_dwordx4 v156, s[22:23]
	s_add_i32 m0, s34, 0x2000
	v_lshl_add_u64 v[250:251], s[22:23], 0, v[160:161]
	s_add_u32 s22, s48, 0xc000
	s_addc_u32 s23, s49, 0
	s_add_i32 s34, s35, s0
	global_load_lds_dwordx4 v[250:251], off
	s_mov_b32 m0, s34
	s_nop 0
	global_load_lds_dwordx4 v156, s[22:23]
	s_add_i32 m0, s34, 0x2000
	s_nop 0
	global_load_lds_dwordx4 v160, s[22:23]
	s_mov_b32 m0, s91
	s_nop 0
	s_add_u32 s100, s50, s92
	s_addc_u32 s101, s51, s93
	global_load_lds_dwordx4 v158, s[100:101]
	s_mov_b32 m0, s30
	s_nop 0
	s_add_u32 s100, s50, s92
	s_addc_u32 s101, s51, s93
	global_load_lds_dwordx4 v162, s[100:101]
	s_waitcnt vmcnt(8)
	s_waitcnt lgkmcnt(0)
	s_barrier
	v_mfma_f32_16x16x32_bf16 v[64:67], v[132:135], v[176:179], v[64:67]
	v_mfma_f32_16x16x32_bf16 v[60:63], v[140:143], v[176:179], v[60:63]
	v_mfma_f32_16x16x32_bf16 v[48:51], v[132:135], v[192:195], v[48:51]
	v_mfma_f32_16x16x32_bf16 v[44:47], v[140:143], v[192:195], v[44:47]
	v_mfma_f32_16x16x32_bf16 v[30:33], v[132:135], v[232:235], v[30:33]
	v_mfma_f32_16x16x32_bf16 v[26:29], v[140:143], v[232:235], v[26:29]
	v_mfma_f32_16x16x32_bf16 v[14:17], v[132:135], v[240:243], v[14:17]
	v_mfma_f32_16x16x32_bf16 v[10:13], v[140:143], v[240:243], v[10:13]
	v_mfma_f32_16x16x32_bf16 v[64:67], v[136:139], v[180:183], v[64:67]
	v_mfma_f32_16x16x32_bf16 v[60:63], v[144:147], v[180:183], v[60:63]
	v_mfma_f32_16x16x32_bf16 v[48:51], v[136:139], v[210:213], v[48:51]
	v_mfma_f32_16x16x32_bf16 v[44:47], v[144:147], v[210:213], v[44:47]
	v_mfma_f32_16x16x32_bf16 v[30:33], v[136:139], v[236:239], v[30:33]
	v_mfma_f32_16x16x32_bf16 v[26:29], v[144:147], v[236:239], v[26:29]
	v_mfma_f32_16x16x32_bf16 v[14:17], v[136:139], v[244:247], v[14:17]
	v_mfma_f32_16x16x32_bf16 v[10:13], v[144:147], v[244:247], v[10:13]
	v_mfma_f32_16x16x32_bf16 v[56:59], v[148:151], v[176:179], v[56:59]
	v_mfma_f32_16x16x32_bf16 v[52:55], v[168:171], v[176:179], v[52:55]
	v_mfma_f32_16x16x32_bf16 v[40:43], v[148:151], v[192:195], v[40:43]
	v_mfma_f32_16x16x32_bf16 v[36:39], v[168:171], v[192:195], v[36:39]
	v_mfma_f32_16x16x32_bf16 v[22:25], v[148:151], v[232:235], v[22:25]
	v_mfma_f32_16x16x32_bf16 v[18:21], v[168:171], v[232:235], v[18:21]
	v_mfma_f32_16x16x32_bf16 v[6:9], v[148:151], v[240:243], v[6:9]
	v_mfma_f32_16x16x32_bf16 v[2:5], v[168:171], v[240:243], v[2:5]
	v_mfma_f32_16x16x32_bf16 v[56:59], v[152:155], v[180:183], v[56:59]
	v_mfma_f32_16x16x32_bf16 v[52:55], v[172:175], v[180:183], v[52:55]
	v_mfma_f32_16x16x32_bf16 v[40:43], v[152:155], v[210:213], v[40:43]
	v_mfma_f32_16x16x32_bf16 v[36:39], v[172:175], v[210:213], v[36:39]
	v_mfma_f32_16x16x32_bf16 v[22:25], v[152:155], v[236:239], v[22:25]
	v_mfma_f32_16x16x32_bf16 v[18:21], v[172:175], v[236:239], v[18:21]
	v_mfma_f32_16x16x32_bf16 v[6:9], v[152:155], v[244:247], v[6:9]
	v_mfma_f32_16x16x32_bf16 v[2:5], v[172:175], v[244:247], v[2:5]
	s_barrier
	s_add_i32 s60, s60, 2
	s_add_u32 s58, s58, 0x10000
	s_addc_u32 s59, s59, 0
	s_cmpk_gt_u32 s60, 0xa9
	s_mov_b64 s[22:23], s[42:43]
	s_cbranch_scc0 .LBB0_1261
	s_and_b64 vcc, exec, s[46:47]
	s_cbranch_vccz .LBB0_1264
	s_barrier
